# P1: skip MFMAs of the zero-padded columns in the k_rope tile column; canonicalizing v_max removed in SB and UP epilogue
# speedup vs baseline: 1.0130x; 1.0047x over previous
; #define PG8_STAGE(bufoff, gbase, voff) do { _Pragma("unroll") for (int _i = 0; _i < 2; ++_i) \
;         __builtin_amdgcn_global_load_lds((const unsigned*)((const char*)(gbase) + (voff)[_i]), (PG8_LAS unsigned*)(lds + (bufoff) + ldsw + _i * 8192), 16, 0, 0); } while (0)
; #define PG8_LDA(dst, b, h) do { _Pragma("unroll") for (int m = 0; m < 4; ++m) _Pragma("unroll") for (int k = 0; k < 2; ++k) dst[m][k] = *(const PG8_LAS bf16x8*)(lds + PG8_SA(b, h) + aoff + m * 2048 + k * 1024); } while (0)
; #define PG8_LDB(dst, b, h) do { _Pragma("unroll") for (int n = 0; n < 2; ++n) _Pragma("unroll") for (int k = 0; k < 2; ++k) dst[n][k] = *(const PG8_LAS bf16x8*)(lds + PG8_SB(b, h) + boff + n * 2048 + k * 1024); } while (0)
; #define PG8_MMA(ai, bj, At, Bt) do { __builtin_amdgcn_s_setprio(1); _Pragma("unroll") for (int m = 0; m < 4; ++m) _Pragma("unroll") for (int n = 0; n < 2; ++n) _Pragma("unroll") for (int k = 0; k < 2; ++k) \
;         acc[ai][bj][m][n] = __builtin_amdgcn_mfma_f32_16x16x32_bf16(Bt[n][k], At[m][k], acc[ai][bj][m][n], 0, 0, 0); __builtin_amdgcn_s_setprio(0); } while (0)
; #define PG8_WAIT_V(n) asm volatile("s_waitcnt vmcnt(" #n ")" ::: "memory")
; #define PG8_WAIT_L(n) asm volatile("s_waitcnt lgkmcnt(" #n ")" ::: "memory")
; #define PG8_BAR __builtin_amdgcn_s_barrier()
; #define PG8_SCHED __builtin_amdgcn_sched_barrier(0)
; template <class Epi, class Sched, bool ALIGN_EPI = false, bool SP2 = false>
; __device__ __forceinline__ void gemm_phase(PG8_LAS unsigned char* lds, const Gemm g, const Sched& S, const Epi& E) {
;     ...
;             PG8_LDB(B0, 0, 0); PG8_LDB(B1, 0, 1); PG8_SCHED; PG8_LDA(At, 0, 0); PG8_STAGE(PG8_SA(1, 1), a1 + hstep, voffA);
;             PG8_WAIT_V(8); PG8_WAIT_L(0); PG8_BAR; PG8_MMA(0, 0, At, B0); PG8_MMA(0, 1, At, B1); PG8_BAR; PG8_SCHED;
;             PG8_LDA(At, 0, 1); PG8_STAGE(PG8_SB(0, 0), b2, voffB); PG8_STAGE(PG8_SB(0, 1), b2 + hstep, voffB); PG8_STAGE(PG8_SA(0, 0), a2, voffA);
;             PG8_WAIT_V(8); PG8_WAIT_L(0); PG8_BAR; PG8_MMA(1, 0, At, B0); PG8_MMA(1, 1, At, B1); PG8_BAR; PG8_SCHED;
.LBB0_217:
	ds_read_b128 v[152:155], v165
	ds_read_b128 v[174:177], v165 offset:1024
	ds_read_b128 v[182:185], v165 offset:2048
	ds_read_b128 v[186:189], v165 offset:3072
	ds_read_b128 v[190:193], v167
	ds_read_b128 v[194:197], v167 offset:1024
	ds_read_b128 v[198:201], v167 offset:2048
	ds_read_b128 v[202:205], v167 offset:3072
	s_add_u32 s12, s10, 0xfff80080
	s_addc_u32 s13, s11, -1
	s_cmp_eq_u32 s49, 28
	s_cselect_b32 s47, s9, s13
	s_cselect_b32 s46, s15, s12
	s_cselect_b32 s13, s33, s48
	s_cselect_b32 s12, s39, s41
	v_lshl_add_u64 v[156:157], s[10:11], 0, v[144:145]
	s_add_i32 m0, s67, 0xc000
	ds_read_b128 v[206:209], v168
	ds_read_b128 v[210:213], v168 offset:1024
	ds_read_b128 v[214:217], v168 offset:2048
	ds_read_b128 v[218:221], v168 offset:3072
	ds_read_b128 v[222:225], v168 offset:4096
	ds_read_b128 v[226:229], v168 offset:5120
	ds_read_b128 v[230:233], v168 offset:6144
	ds_read_b128 v[234:237], v168 offset:7168
	global_load_lds_dwordx4 v[156:157], off
	v_lshl_add_u64 v[156:157], s[10:11], 0, v[146:147]
	s_add_i32 m0, s67, 0xe000
	s_nop 0
	global_load_lds_dwordx4 v[156:157], off
	s_waitcnt vmcnt(8)
	s_waitcnt lgkmcnt(0)
	s_barrier
	s_setprio 1
	s_waitcnt lgkmcnt(0)
	v_mfma_f32_16x16x32_bf16 v[124:127], v[152:155], v[206:209], v[124:127]
	v_mfma_f32_16x16x32_bf16 v[120:123], v[182:185], v[206:209], v[120:123]
	v_mfma_f32_16x16x32_bf16 v[108:111], v[152:155], v[214:217], v[108:111]
	v_mfma_f32_16x16x32_bf16 v[104:107], v[182:185], v[214:217], v[104:107]
	v_mfma_f32_16x16x32_bf16 v[92:95], v[152:155], v[222:225], v[92:95]
	v_mfma_f32_16x16x32_bf16 v[88:91], v[182:185], v[222:225], v[88:91]
	v_mfma_f32_16x16x32_bf16 v[76:79], v[152:155], v[230:233], v[76:79]
	v_mfma_f32_16x16x32_bf16 v[72:75], v[182:185], v[230:233], v[72:75]
	v_mfma_f32_16x16x32_bf16 v[124:127], v[174:177], v[210:213], v[124:127]
	v_mfma_f32_16x16x32_bf16 v[120:123], v[186:189], v[210:213], v[120:123]
	v_mfma_f32_16x16x32_bf16 v[108:111], v[174:177], v[218:221], v[108:111]
	v_mfma_f32_16x16x32_bf16 v[104:107], v[186:189], v[218:221], v[104:107]
	v_mfma_f32_16x16x32_bf16 v[92:95], v[174:177], v[226:229], v[92:95]
	v_mfma_f32_16x16x32_bf16 v[88:91], v[186:189], v[226:229], v[88:91]
	v_mfma_f32_16x16x32_bf16 v[76:79], v[174:177], v[234:237], v[76:79]
	v_mfma_f32_16x16x32_bf16 v[72:75], v[186:189], v[234:237], v[72:75]
	s_setprio 0
	s_cmp_eq_u32 s14, 16
	s_cbranch_scc1 .Lp1_skipb1_0
	s_setprio 1
	v_mfma_f32_16x16x32_bf16 v[116:119], v[190:193], v[206:209], v[116:119]
	v_mfma_f32_16x16x32_bf16 v[112:115], v[198:201], v[206:209], v[112:115]
	v_mfma_f32_16x16x32_bf16 v[100:103], v[190:193], v[214:217], v[100:103]
	v_mfma_f32_16x16x32_bf16 v[96:99], v[198:201], v[214:217], v[96:99]
	v_mfma_f32_16x16x32_bf16 v[84:87], v[190:193], v[222:225], v[84:87]
	v_mfma_f32_16x16x32_bf16 v[80:83], v[198:201], v[222:225], v[80:83]
	v_mfma_f32_16x16x32_bf16 v[68:71], v[190:193], v[230:233], v[68:71]
	v_mfma_f32_16x16x32_bf16 v[64:67], v[198:201], v[230:233], v[64:67]
	v_mfma_f32_16x16x32_bf16 v[116:119], v[194:197], v[210:213], v[116:119]
	v_mfma_f32_16x16x32_bf16 v[112:115], v[202:205], v[210:213], v[112:115]
	v_mfma_f32_16x16x32_bf16 v[100:103], v[194:197], v[218:221], v[100:103]
	v_mfma_f32_16x16x32_bf16 v[96:99], v[202:205], v[218:221], v[96:99]
	v_mfma_f32_16x16x32_bf16 v[84:87], v[194:197], v[226:229], v[84:87]
	v_mfma_f32_16x16x32_bf16 v[80:83], v[202:205], v[226:229], v[80:83]
	v_mfma_f32_16x16x32_bf16 v[68:71], v[194:197], v[234:237], v[68:71]
	v_mfma_f32_16x16x32_bf16 v[64:67], v[202:205], v[234:237], v[64:67]
	s_setprio 0
.Lp1_skipb1_0:
	s_barrier
	s_add_i32 s50, s79, s66
	v_lshl_add_u64 v[156:157], s[12:13], 0, v[130:131]
	s_mov_b32 m0, s50
	ds_read_b128 v[206:209], v168 offset:16384
	ds_read_b128 v[210:213], v168 offset:17408
	ds_read_b128 v[214:217], v168 offset:18432
	ds_read_b128 v[218:221], v168 offset:19456
	ds_read_b128 v[222:225], v168 offset:20480
	ds_read_b128 v[226:229], v168 offset:21504
	ds_read_b128 v[230:233], v168 offset:22528
	ds_read_b128 v[234:237], v168 offset:23552
	global_load_lds_dwordx4 v[156:157], off
	s_add_i32 m0, s50, 0x2000
	s_add_u32 s50, s12, 0x80000
	v_lshl_add_u64 v[238:239], s[12:13], 0, v[134:135]
	s_addc_u32 s51, s13, 0
	s_add_i32 s52, s72, s66
	global_load_lds_dwordx4 v[238:239], off
	v_lshl_add_u64 v[240:241], s[50:51], 0, v[130:131]
	s_mov_b32 m0, s52
	v_lshl_add_u64 v[242:243], s[46:47], 0, v[132:133]
	global_load_lds_dwordx4 v[240:241], off
	v_lshl_add_u64 v[240:241], s[50:51], 0, v[134:135]
	s_add_i32 m0, s52, 0x2000
	s_nop 0
	global_load_lds_dwordx4 v[240:241], off
	v_lshl_add_u64 v[240:241], s[46:47], 0, v[128:129]
	s_mov_b32 m0, s67
	s_nop 0
	global_load_lds_dwordx4 v[240:241], off
	s_mov_b32 m0, s68
	s_nop 0
	global_load_lds_dwordx4 v[242:243], off
	s_waitcnt vmcnt(8)
	s_waitcnt lgkmcnt(0)
	s_barrier
	s_setprio 1
	s_waitcnt lgkmcnt(0)
	v_mfma_f32_16x16x32_bf16 v[60:63], v[152:155], v[206:209], v[60:63]
	v_mfma_f32_16x16x32_bf16 v[56:59], v[182:185], v[206:209], v[56:59]
	v_mfma_f32_16x16x32_bf16 v[44:47], v[152:155], v[214:217], v[44:47]
	v_mfma_f32_16x16x32_bf16 v[40:43], v[182:185], v[214:217], v[40:43]
	v_mfma_f32_16x16x32_bf16 v[28:31], v[152:155], v[222:225], v[28:31]
	v_mfma_f32_16x16x32_bf16 v[24:27], v[182:185], v[222:225], v[24:27]
	v_mfma_f32_16x16x32_bf16 v[12:15], v[152:155], v[230:233], v[12:15]
	v_mfma_f32_16x16x32_bf16 v[8:11], v[182:185], v[230:233], v[8:11]
	v_mfma_f32_16x16x32_bf16 v[60:63], v[174:177], v[210:213], v[60:63]
	v_mfma_f32_16x16x32_bf16 v[56:59], v[186:189], v[210:213], v[56:59]
	v_mfma_f32_16x16x32_bf16 v[44:47], v[174:177], v[218:221], v[44:47]
	v_mfma_f32_16x16x32_bf16 v[40:43], v[186:189], v[218:221], v[40:43]
	v_mfma_f32_16x16x32_bf16 v[28:31], v[174:177], v[226:229], v[28:31]
	v_mfma_f32_16x16x32_bf16 v[24:27], v[186:189], v[226:229], v[24:27]
	v_mfma_f32_16x16x32_bf16 v[12:15], v[174:177], v[234:237], v[12:15]
	v_mfma_f32_16x16x32_bf16 v[8:11], v[186:189], v[234:237], v[8:11]
	s_setprio 0
	s_cmp_eq_u32 s14, 16
	s_cbranch_scc1 .Lp1_skipb1_1
; #define PG8_STAGE(bufoff, gbase, voff) do { _Pragma("unroll") for (int _i = 0; _i < 2; ++_i) \
;         __builtin_amdgcn_global_load_lds((const unsigned*)((const char*)(gbase) + (voff)[_i]), (PG8_LAS unsigned*)(lds + (bufoff) + ldsw + _i * 8192), 16, 0, 0); } while (0)
; #define PG8_LDA(dst, b, h) do { _Pragma("unroll") for (int m = 0; m < 4; ++m) _Pragma("unroll") for (int k = 0; k < 2; ++k) dst[m][k] = *(const PG8_LAS bf16x8*)(lds + PG8_SA(b, h) + aoff + m * 2048 + k * 1024); } while (0)
; #define PG8_LDB(dst, b, h) do { _Pragma("unroll") for (int n = 0; n < 2; ++n) _Pragma("unroll") for (int k = 0; k < 2; ++k) dst[n][k] = *(const PG8_LAS bf16x8*)(lds + PG8_SB(b, h) + boff + n * 2048 + k * 1024); } while (0)
; #define PG8_MMA(ai, bj, At, Bt) do { __builtin_amdgcn_s_setprio(1); _Pragma("unroll") for (int m = 0; m < 4; ++m) _Pragma("unroll") for (int n = 0; n < 2; ++n) _Pragma("unroll") for (int k = 0; k < 2; ++k) \
;         acc[ai][bj][m][n] = __builtin_amdgcn_mfma_f32_16x16x32_bf16(Bt[n][k], At[m][k], acc[ai][bj][m][n], 0, 0, 0); __builtin_amdgcn_s_setprio(0); } while (0)
; #define PG8_WAIT_V(n) asm volatile("s_waitcnt vmcnt(" #n ")" ::: "memory")
; #define PG8_WAIT_L(n) asm volatile("s_waitcnt lgkmcnt(" #n ")" ::: "memory")
; #define PG8_BAR __builtin_amdgcn_s_barrier()
; #define PG8_SCHED __builtin_amdgcn_sched_barrier(0)
; template <class Epi, class Sched, bool ALIGN_EPI = false, bool SP2 = false>
; __device__ __forceinline__ void gemm_phase(PG8_LAS unsigned char* lds, const Gemm g, const Sched& S, const Epi& E) {
;     ...
;             PG8_LDA(At, 0, 1); PG8_STAGE(PG8_SB(0, 0), b2, voffB); PG8_STAGE(PG8_SB(0, 1), b2 + hstep, voffB); PG8_STAGE(PG8_SA(0, 0), a2, voffA);
;             PG8_WAIT_V(8); PG8_WAIT_L(0); PG8_BAR; PG8_MMA(1, 0, At, B0); PG8_MMA(1, 1, At, B1); PG8_BAR; PG8_SCHED;
;             PG8_LDB(B0, 1, 0); PG8_LDB(B1, 1, 1); PG8_SCHED; PG8_LDA(At, 1, 0); PG8_STAGE(PG8_SA(0, 1), a2 + hstep, voffA);
;             PG8_WAIT_V(8); PG8_WAIT_L(0); PG8_BAR; PG8_MMA(0, 0, At, B0); PG8_MMA(0, 1, At, B1); PG8_BAR; PG8_SCHED;
	s_setprio 1
	v_mfma_f32_16x16x32_bf16 v[52:55], v[190:193], v[206:209], v[52:55]
	v_mfma_f32_16x16x32_bf16 v[48:51], v[198:201], v[206:209], v[48:51]
	v_mfma_f32_16x16x32_bf16 v[36:39], v[190:193], v[214:217], v[36:39]
	v_mfma_f32_16x16x32_bf16 v[32:35], v[198:201], v[214:217], v[32:35]
	v_mfma_f32_16x16x32_bf16 v[20:23], v[190:193], v[222:225], v[20:23]
	v_mfma_f32_16x16x32_bf16 v[16:19], v[198:201], v[222:225], v[16:19]
	v_mfma_f32_16x16x32_bf16 v[4:7], v[190:193], v[230:233], v[4:7]
	v_mfma_f32_16x16x32_bf16 v[0:3], v[198:201], v[230:233], v[0:3]
	v_mfma_f32_16x16x32_bf16 v[52:55], v[194:197], v[210:213], v[52:55]
	v_mfma_f32_16x16x32_bf16 v[48:51], v[202:205], v[210:213], v[48:51]
	v_mfma_f32_16x16x32_bf16 v[36:39], v[194:197], v[218:221], v[36:39]
	v_mfma_f32_16x16x32_bf16 v[32:35], v[202:205], v[218:221], v[32:35]
	v_mfma_f32_16x16x32_bf16 v[20:23], v[194:197], v[226:229], v[20:23]
	v_mfma_f32_16x16x32_bf16 v[16:19], v[202:205], v[226:229], v[16:19]
	v_mfma_f32_16x16x32_bf16 v[4:7], v[194:197], v[234:237], v[4:7]
	v_mfma_f32_16x16x32_bf16 v[0:3], v[202:205], v[234:237], v[0:3]
	s_setprio 0
.Lp1_skipb1_1:
	s_barrier
	s_add_i32 s50, 0, 0x18000
	v_add_u32_e32 v136, s50, v141
	s_add_i32 s51, 0, 0x1c000
	ds_read_b128 v[152:155], v136
	ds_read_b128 v[174:177], v136 offset:1024
	ds_read_b128 v[182:185], v136 offset:2048
	ds_read_b128 v[186:189], v136 offset:3072
	v_add_u32_e32 v136, s51, v141
	ds_read_b128 v[190:193], v136
	ds_read_b128 v[194:197], v136 offset:1024
	ds_read_b128 v[198:201], v136 offset:2048
	ds_read_b128 v[202:205], v136 offset:3072
	s_add_u32 s46, s46, 0x80000
	s_addc_u32 s47, s47, 0
	s_mov_b32 m0, s69
	v_lshl_add_u64 v[244:245], s[46:47], 0, v[128:129]
	ds_read_b128 v[206:209], v168 offset:32768
	ds_read_b128 v[210:213], v168 offset:33792
	ds_read_b128 v[214:217], v168 offset:34816
	ds_read_b128 v[218:221], v168 offset:35840
	ds_read_b128 v[222:225], v168 offset:36864
	ds_read_b128 v[226:229], v168 offset:37888
	ds_read_b128 v[230:233], v168 offset:38912
	ds_read_b128 v[234:237], v168 offset:39936
	global_load_lds_dwordx4 v[244:245], off
	v_lshl_add_u64 v[244:245], s[46:47], 0, v[132:133]
	s_mov_b32 m0, s70
	s_nop 0
	global_load_lds_dwordx4 v[244:245], off
	s_waitcnt vmcnt(8)
	s_waitcnt lgkmcnt(0)
	s_barrier
	s_setprio 1
	s_waitcnt lgkmcnt(0)
	v_mfma_f32_16x16x32_bf16 v[124:127], v[152:155], v[206:209], v[124:127]
	v_mfma_f32_16x16x32_bf16 v[120:123], v[182:185], v[206:209], v[120:123]
	v_mfma_f32_16x16x32_bf16 v[108:111], v[152:155], v[214:217], v[108:111]
	v_mfma_f32_16x16x32_bf16 v[104:107], v[182:185], v[214:217], v[104:107]
	v_mfma_f32_16x16x32_bf16 v[92:95], v[152:155], v[222:225], v[92:95]
	v_mfma_f32_16x16x32_bf16 v[88:91], v[182:185], v[222:225], v[88:91]
	v_mfma_f32_16x16x32_bf16 v[76:79], v[152:155], v[230:233], v[76:79]
	v_mfma_f32_16x16x32_bf16 v[72:75], v[182:185], v[230:233], v[72:75]
	v_mfma_f32_16x16x32_bf16 v[124:127], v[174:177], v[210:213], v[124:127]
	v_mfma_f32_16x16x32_bf16 v[120:123], v[186:189], v[210:213], v[120:123]
	v_mfma_f32_16x16x32_bf16 v[108:111], v[174:177], v[218:221], v[108:111]
	v_mfma_f32_16x16x32_bf16 v[104:107], v[186:189], v[218:221], v[104:107]
	v_mfma_f32_16x16x32_bf16 v[92:95], v[174:177], v[226:229], v[92:95]
	v_mfma_f32_16x16x32_bf16 v[88:91], v[186:189], v[226:229], v[88:91]
	v_mfma_f32_16x16x32_bf16 v[76:79], v[174:177], v[234:237], v[76:79]
	v_mfma_f32_16x16x32_bf16 v[72:75], v[186:189], v[234:237], v[72:75]
	s_setprio 0
	s_cmp_eq_u32 s14, 16
	s_cbranch_scc1 .Lp1_skipb1_2
	s_setprio 1
	v_mfma_f32_16x16x32_bf16 v[116:119], v[190:193], v[206:209], v[116:119]
	v_mfma_f32_16x16x32_bf16 v[112:115], v[198:201], v[206:209], v[112:115]
	v_mfma_f32_16x16x32_bf16 v[100:103], v[190:193], v[214:217], v[100:103]
	v_mfma_f32_16x16x32_bf16 v[96:99], v[198:201], v[214:217], v[96:99]
	v_mfma_f32_16x16x32_bf16 v[84:87], v[190:193], v[222:225], v[84:87]
	v_mfma_f32_16x16x32_bf16 v[80:83], v[198:201], v[222:225], v[80:83]
	v_mfma_f32_16x16x32_bf16 v[68:71], v[190:193], v[230:233], v[68:71]
	v_mfma_f32_16x16x32_bf16 v[64:67], v[198:201], v[230:233], v[64:67]
	v_mfma_f32_16x16x32_bf16 v[116:119], v[194:197], v[210:213], v[116:119]
	v_mfma_f32_16x16x32_bf16 v[112:115], v[202:205], v[210:213], v[112:115]
	v_mfma_f32_16x16x32_bf16 v[100:103], v[194:197], v[218:221], v[100:103]
	v_mfma_f32_16x16x32_bf16 v[96:99], v[202:205], v[218:221], v[96:99]
	v_mfma_f32_16x16x32_bf16 v[84:87], v[194:197], v[226:229], v[84:87]
	v_mfma_f32_16x16x32_bf16 v[80:83], v[202:205], v[226:229], v[80:83]
	v_mfma_f32_16x16x32_bf16 v[68:71], v[194:197], v[234:237], v[68:71]
	v_mfma_f32_16x16x32_bf16 v[64:67], v[202:205], v[234:237], v[64:67]
	s_setprio 0
; #define PG8_STAGE(bufoff, gbase, voff) do { _Pragma("unroll") for (int _i = 0; _i < 2; ++_i) \
;         __builtin_amdgcn_global_load_lds((const unsigned*)((const char*)(gbase) + (voff)[_i]), (PG8_LAS unsigned*)(lds + (bufoff) + ldsw + _i * 8192), 16, 0, 0); } while (0)
; #define PG8_LDA(dst, b, h) do { _Pragma("unroll") for (int m = 0; m < 4; ++m) _Pragma("unroll") for (int k = 0; k < 2; ++k) dst[m][k] = *(const PG8_LAS bf16x8*)(lds + PG8_SA(b, h) + aoff + m * 2048 + k * 1024); } while (0)
; #define PG8_MMA(ai, bj, At, Bt) do { __builtin_amdgcn_s_setprio(1); _Pragma("unroll") for (int m = 0; m < 4; ++m) _Pragma("unroll") for (int n = 0; n < 2; ++n) _Pragma("unroll") for (int k = 0; k < 2; ++k) \
;         acc[ai][bj][m][n] = __builtin_amdgcn_mfma_f32_16x16x32_bf16(Bt[n][k], At[m][k], acc[ai][bj][m][n], 0, 0, 0); __builtin_amdgcn_s_setprio(0); } while (0)
; #define PG8_WAIT_V(n) asm volatile("s_waitcnt vmcnt(" #n ")" ::: "memory")
; #define PG8_WAIT_L(n) asm volatile("s_waitcnt lgkmcnt(" #n ")" ::: "memory")
; #define PG8_BAR __builtin_amdgcn_s_barrier()
; #define PG8_SCHED __builtin_amdgcn_sched_barrier(0)
; template <class Epi, class Sched, bool ALIGN_EPI = false, bool SP2 = false>
; __device__ __forceinline__ void gemm_phase(PG8_LAS unsigned char* lds, const Gemm g, const Sched& S, const Epi& E) {
;     ...
;         for (int t = 0; t < nt; t += 2) {
;             const bool last = (t == nt - 2);
;             const char* a1 = cA + (size_t)(t + 1) * kstep;
;             const char* a2 = last ? nA : cA + (size_t)(t + 2) * kstep; const char* b2 = last ? nB : cB + (size_t)(t + 2) * kstep;
;     ...
;             PG8_LDA(At, 0, 1); PG8_STAGE(PG8_SB(0, 0), b2, voffB); PG8_STAGE(PG8_SB(0, 1), b2 + hstep, voffB); PG8_STAGE(PG8_SA(0, 0), a2, voffA);
;             PG8_WAIT_V(8); PG8_WAIT_L(0); PG8_BAR; PG8_MMA(1, 0, At, B0); PG8_MMA(1, 1, At, B1); PG8_BAR; PG8_SCHED;
.Lp1_skipb1_2:
	s_barrier
	s_add_i32 s46, s50, s66
	v_lshl_add_u64 v[156:157], v[156:157], 0, s[26:27]
	s_mov_b32 m0, s46
	ds_read_b128 v[206:209], v168 offset:49152
	ds_read_b128 v[210:213], v168 offset:50176
	ds_read_b128 v[214:217], v168 offset:51200
	ds_read_b128 v[218:221], v168 offset:52224
	ds_read_b128 v[222:225], v168 offset:53248
	ds_read_b128 v[226:229], v168 offset:54272
	ds_read_b128 v[230:233], v168 offset:55296
	ds_read_b128 v[234:237], v168 offset:56320
	global_load_lds_dwordx4 v[156:157], off
	s_add_i32 m0, s46, 0x2000
	s_add_u32 s12, s12, 0x80080
	v_lshl_add_u64 v[156:157], v[238:239], 0, s[26:27]
	s_addc_u32 s13, s13, 0
	s_add_i32 s46, s51, s66
	global_load_lds_dwordx4 v[156:157], off
	v_lshl_add_u64 v[156:157], s[12:13], 0, v[130:131]
	s_mov_b32 m0, s46
	s_nop 0
	global_load_lds_dwordx4 v[156:157], off
	v_lshl_add_u64 v[156:157], s[12:13], 0, v[134:135]
	s_add_i32 m0, s46, 0x2000
	s_nop 0
	global_load_lds_dwordx4 v[156:157], off
	v_lshl_add_u64 v[156:157], v[240:241], 0, s[26:27]
	s_mov_b32 m0, s95
	s_nop 0
	global_load_lds_dwordx4 v[156:157], off
	v_lshl_add_u64 v[156:157], v[242:243], 0, s[26:27]
	s_mov_b32 m0, s96
	s_nop 0
	global_load_lds_dwordx4 v[156:157], off
	s_waitcnt vmcnt(8)
	s_waitcnt lgkmcnt(0)
	s_barrier
	s_setprio 1
	s_waitcnt lgkmcnt(0)
	v_mfma_f32_16x16x32_bf16 v[60:63], v[152:155], v[206:209], v[60:63]
	v_mfma_f32_16x16x32_bf16 v[56:59], v[182:185], v[206:209], v[56:59]
	v_mfma_f32_16x16x32_bf16 v[44:47], v[152:155], v[214:217], v[44:47]
	v_mfma_f32_16x16x32_bf16 v[40:43], v[182:185], v[214:217], v[40:43]
	v_mfma_f32_16x16x32_bf16 v[28:31], v[152:155], v[222:225], v[28:31]
	v_mfma_f32_16x16x32_bf16 v[24:27], v[182:185], v[222:225], v[24:27]
	v_mfma_f32_16x16x32_bf16 v[12:15], v[152:155], v[230:233], v[12:15]
	v_mfma_f32_16x16x32_bf16 v[8:11], v[182:185], v[230:233], v[8:11]
	v_mfma_f32_16x16x32_bf16 v[60:63], v[174:177], v[210:213], v[60:63]
	v_mfma_f32_16x16x32_bf16 v[56:59], v[186:189], v[210:213], v[56:59]
	v_mfma_f32_16x16x32_bf16 v[44:47], v[174:177], v[218:221], v[44:47]
	v_mfma_f32_16x16x32_bf16 v[40:43], v[186:189], v[218:221], v[40:43]
	v_mfma_f32_16x16x32_bf16 v[28:31], v[174:177], v[226:229], v[28:31]
	v_mfma_f32_16x16x32_bf16 v[24:27], v[186:189], v[226:229], v[24:27]
	v_mfma_f32_16x16x32_bf16 v[12:15], v[174:177], v[234:237], v[12:15]
	v_mfma_f32_16x16x32_bf16 v[8:11], v[186:189], v[234:237], v[8:11]
	s_setprio 0
	s_cmp_eq_u32 s14, 16
	s_cbranch_scc1 .Lp1_skipb1_3
	s_setprio 1
	v_mfma_f32_16x16x32_bf16 v[52:55], v[190:193], v[206:209], v[52:55]
	v_mfma_f32_16x16x32_bf16 v[48:51], v[198:201], v[206:209], v[48:51]
	v_mfma_f32_16x16x32_bf16 v[36:39], v[190:193], v[214:217], v[36:39]
	v_mfma_f32_16x16x32_bf16 v[32:35], v[198:201], v[214:217], v[32:35]
	v_mfma_f32_16x16x32_bf16 v[20:23], v[190:193], v[222:225], v[20:23]
	v_mfma_f32_16x16x32_bf16 v[16:19], v[198:201], v[222:225], v[16:19]
	v_mfma_f32_16x16x32_bf16 v[4:7], v[190:193], v[230:233], v[4:7]
	v_mfma_f32_16x16x32_bf16 v[0:3], v[198:201], v[230:233], v[0:3]
	v_mfma_f32_16x16x32_bf16 v[52:55], v[194:197], v[210:213], v[52:55]
	v_mfma_f32_16x16x32_bf16 v[48:51], v[202:205], v[210:213], v[48:51]
	v_mfma_f32_16x16x32_bf16 v[36:39], v[194:197], v[218:221], v[36:39]
	v_mfma_f32_16x16x32_bf16 v[32:35], v[202:205], v[218:221], v[32:35]
	v_mfma_f32_16x16x32_bf16 v[20:23], v[194:197], v[226:229], v[20:23]
	v_mfma_f32_16x16x32_bf16 v[16:19], v[202:205], v[226:229], v[16:19]
	v_mfma_f32_16x16x32_bf16 v[4:7], v[194:197], v[234:237], v[4:7]
	v_mfma_f32_16x16x32_bf16 v[0:3], v[202:205], v[234:237], v[0:3]
	s_setprio 0
.Lp1_skipb1_3:
	s_barrier
	s_add_i32 s49, s49, 2
	s_add_u32 s10, s10, 0x100
	s_addc_u32 s11, s11, 0
	s_add_u32 s41, s41, 0x100
	s_addc_u32 s48, s48, 0
	s_cmp_gt_u32 s49, 29
	s_cbranch_scc0 .LBB0_217
	s_and_b64 vcc, exec, s[28:29]
	s_cbranch_vccz .LBB0_220
	s_barrier

; __device__ __forceinline__ void load8(const bf16_t* src, float* v) { const u32x4 w = *(const u32x4*)src; v[0] = bf_lo(w.x); v[1] = bf_hi(w.x); v[2] = bf_lo(w.y); v[3] = bf_hi(w.y); v[4] = bf_lo(w.z); v[5] = bf_hi(w.z); v[6] = bf_lo(w.w); v[7] = bf_hi(w.w); }
; __device__ __forceinline__ int v_st(int k, int c) { const int kk = (k & ~0xC) | ((k & 4) << 1) | ((k & 8) >> 1); return ((kk >> 3) * 4 + (c >> 5)) * 512 + ((kk & 7) * 32 + (c & 31)) * 2; }
; __device__ __forceinline__ int v_rd_base(int lane) { return ((lane & 3) << 3) | (((lane >> 2) & 3) << 6) | (((lane >> 4) & 1) << 5) | (((lane >> 5) & 1) << 8); }
; __device__ __forceinline__ void sb_block(const bf16* Qb, const bf16* Kh, const bf16* Vh, bf16* Ob, int q0, char* lds) {
;     int tid_ = threadIdx.x; asm volatile("" : "+v"(tid_));
;     const int tid = tid_, wid = __builtin_amdgcn_readfirstlane(tid >> 6), lane = tid & 63, r32 = lane & 31, hi = lane >> 5;
;     char* V_lds = lds; char* K_lds = lds + 2 * SHM_V; volatile __attribute__((address_space(3))) int* flags = (volatile __attribute__((address_space(3))) int*)(lds + 2 * SHM_V + 2 * SHM_K);
;     const int sr = tid >> 4, sc = (tid & 15) * 8, vst0 = v_st(sr, sc), vst1 = v_st(32 + sr, sc), kws = KSWZ(sr, sc * 2);
;     const int vb0 = (int)(uintptr_t)V_lds + v_rd_base(lane);
;     bf16x8 qr[8];
; #pragma unroll
;     for (int d0 = 0; d0 < 8; ++d0) qr[d0] = load8<bf16>(Qb + (size_t)(wid * QBLK + r32) * D + d0 * 16 + hi * 8);
;     const int qlo = q0 + wid * QBLK, trow = qlo + r32;
;     float R = 0.f; f32x16 o[4] = {};
;     bool wdone = false;
;     bf16x8 st_v0, st_v1, st_k0, st_k1;
;     ...
;     int j = q0 / KVBLK + 3;
;     SBLOAD(j * KVBLK);
;     for (int it = 0; ; ++it, --j) {
;         const int buf = it & 1;
;         VMW();
;         *(bf16x8*)(V_lds + buf * SHM_V + vst0) = st_v0; *(bf16x8*)(V_lds + buf * SHM_V + vst1) = st_v1;
;         *(bf16x8*)(K_lds + buf * SHM_K + kws) = st_k0; *(bf16x8*)(K_lds + buf * SHM_K + kws + 32 * 256) = st_k1;
;         __syncthreads();
;         if (it > 0) { int all = 1;
; #pragma unroll
;             for (int w = 0; w < 8; ++w) all &= flags[((it - 1) & 1) * 8 + w];
;             if (__builtin_amdgcn_readfirstlane(all)) break; }
;         if (j > 0) SBLOAD((j - 1) * KVBLK);
;         const int kb = j * KVBLK;
;         const bool act = !wdone && (kb < qlo + QBLK - 1);
.LBB0_685:
	s_mov_b64 s[4:5], s[0:1]
	s_load_dwordx2 s[4:5], s[4:5], 0xa8
	s_ashr_i32 s88, s81, 5
	s_lshl_b32 s6, s81, 8
	s_ashr_i32 s89, s88, 31
	s_and_b32 s83, s6, 0x1f00
	s_lshl_b64 s[70:71], s[88:89], 21
	s_lshl_b32 s6, s83, 8
	s_waitcnt lgkmcnt(0)
	s_add_u32 s4, s4, s70
	s_addc_u32 s7, s5, s71
	s_add_u32 s6, s4, s6
	s_mov_b64 s[4:5], s[0:1]
	s_load_dwordx2 s[4:5], s[4:5], 0xa8
	s_mov_b64 s[8:9], s[0:1]
	s_addc_u32 s7, s7, 0
	s_load_dwordx2 s[8:9], s[8:9], 0xa8
	s_waitcnt lgkmcnt(0)
	s_add_u32 s94, s4, 0x14000000
	s_addc_u32 s95, s5, 0
	s_add_u32 s4, s94, s70
	s_addc_u32 s5, s95, s71
	s_add_u32 s96, s8, 0x18000000
	s_addc_u32 s97, s9, 0
	s_mov_b64 s[10:11], s[0:1]
	s_add_u32 s8, s96, s70
	v_mov_b32_e32 v181, v178
	s_addc_u32 s9, s97, s71
	s_load_dwordx2 s[90:91], s[10:11], 0xa8
	s_or_b32 s10, s83, 0xc0
	v_ashrrev_i32_e32 v66, 4, v181
	v_add_u32_e32 v20, s10, v66
	v_lshlrev_b32_e32 v26, 3, v181
	v_ashrrev_i32_e32 v21, 31, v20
	v_and_b32_e32 v0, 0x78, v26
	v_lshlrev_b64 v[10:11], 8, v[20:21]
	v_lshlrev_b32_e32 v18, 1, v0
	v_lshl_add_u64 v[2:3], s[8:9], 0, v[10:11]
	v_mov_b32_e32 v19, v1
	v_add_u32_e32 v0, s83, v66
	v_lshl_add_u64 v[12:13], v[2:3], 0, v[18:19]
	v_add_u32_e32 v2, 0xe0, v0
	v_ashrrev_i32_e32 v3, 31, v2
	v_lshlrev_b64 v[14:15], 8, v[2:3]
	v_lshl_add_u64 v[2:3], s[8:9], 0, v[14:15]
	v_lshl_add_u64 v[10:11], s[4:5], 0, v[10:11]
	v_lshl_add_u64 v[16:17], v[2:3], 0, v[18:19]
	global_load_dwordx4 v[2:5], v[12:13], off
	global_load_dwordx4 v[6:9], v[16:17], off
	v_lshl_add_u64 v[22:23], v[10:11], 0, v[18:19]
	v_lshl_add_u64 v[10:11], s[4:5], 0, v[14:15]
	v_lshl_add_u64 v[24:25], v[10:11], 0, v[18:19]
	global_load_dwordx4 v[10:13], v[22:23], off
	global_load_dwordx4 v[14:17], v[24:25], off
	v_and_b32_e32 v0, 0xfffff0, v66
	v_lshlrev_b32_e32 v21, 1, v66
	v_and_or_b32 v0, v21, 8, v0
	v_lshrrev_b32_e32 v0, 1, v0
	v_bfe_u32 v22, v26, 5, 2
	v_lshrrev_b32_e32 v21, 1, v66
	v_or_b32_e32 v27, v0, v22
	v_and_b32_e32 v0, 3, v66
	v_and_or_b32 v21, v21, 4, v0
	v_add_u32_e32 v0, 32, v66
	v_readfirstlane_b32 s11, v181
	v_and_b32_e32 v23, 0xfffff0, v0
	v_lshlrev_b32_e32 v0, 1, v0
	s_ashr_i32 s76, s11, 6
	v_and_or_b32 v0, v0, 8, v23
	v_and_b32_e32 v182, 31, v181
	v_lshrrev_b32_e32 v0, 1, v0
	s_lshl_b32 s92, s76, 5
	v_or_b32_e32 v28, v0, v22
	v_or_b32_e32 v22, s92, v182
	v_ashrrev_i32_e32 v23, 31, v22
	v_bfe_u32 v183, v181, 5, 1
	v_lshlrev_b64 v[22:23], 8, v[22:23]
	v_lshl_add_u64 v[22:23], s[6:7], 0, v[22:23]
	v_lshlrev_b32_e32 v0, 4, v183
	v_lshl_add_u64 v[22:23], v[22:23], 0, v[0:1]
	s_mov_b64 s[6:7], 0x10000000
	v_lshl_add_u64 v[24:25], v[22:23], 0, s[6:7]
	s_brev_b32 s6, 8
	v_lshlrev_b32_e32 v185, 9, v27
	v_and_b32_e32 v186, 48, v18
	v_lshl_add_u32 v189, v21, 6, 0
	v_add_co_u32_e32 v22, vcc, s6, v22
	v_lshlrev_b32_e32 v187, 9, v28
	v_add3_u32 v21, v189, v185, v186
	v_bitop3_b32 v184, v18, v181, s78 bitop3:0x78
	v_addc_co_u32_e32 v23, vcc, 0, v23, vcc
	global_load_dwordx4 v[98:101], v[24:25], off offset:32
	global_load_dwordx4 v[102:105], v[24:25], off offset:64
	global_load_dwordx4 v[106:109], v[24:25], off offset:96
	global_load_dwordx4 v[110:113], v[24:25], off offset:128
	global_load_dwordx4 v[114:117], v[24:25], off offset:160
	global_load_dwordx4 v[118:121], v[24:25], off offset:192
	global_load_dwordx4 v[122:125], v[22:23], off
	global_load_dwordx4 v[126:129], v[24:25], off offset:224
	v_lshlrev_b32_e32 v188, 8, v66
	s_waitcnt vmcnt(0)
	v_lshl_add_u64 v[22:23], s[8:9], 0, v[18:19]
	v_lshl_add_u64 v[18:19], s[4:5], 0, v[18:19]
	s_add_i32 s4, s92, s83
	s_or_b32 s85, s4, 31
	s_movk_i32 s5, 0x118
	s_cmp_lg_u32 0, -1
	v_and_b32_e32 v67, 63, v181
	v_or_b32_e32 v190, s4, v182
	s_movk_i32 s4, 0x60
	s_cselect_b32 s6, 0, 0
	v_lshlrev_b32_e32 v191, 8, v182
	v_lshlrev_b32_e32 v196, 2, v183
	s_cmp_ge_i32 s10, s85
	s_waitcnt vmcnt(11)
	ds_write_b128 v21, v[2:5]
	v_add3_u32 v2, v189, v187, v186
	s_waitcnt vmcnt(10)
	ds_write_b128 v2, v[6:9]
	v_add3_u32 v2, 0, v188, v184
	s_waitcnt vmcnt(9)
	ds_write_b128 v2, v[10:13] offset:32768
	s_waitcnt vmcnt(8)
	ds_write_b128 v2, v[14:17] offset:40960
	v_subrev_u32_e32 v2, 64, v20
	v_ashrrev_i32_e32 v3, 31, v2
	v_subrev_u32_e32 v6, 32, v20
	v_lshlrev_b64 v[2:3], 8, v[2:3]
	v_ashrrev_i32_e32 v7, 31, v6
	v_lshl_add_u64 v[4:5], v[22:23], 0, v[2:3]
	v_lshlrev_b64 v[6:7], 8, v[6:7]
	v_lshl_add_u64 v[2:3], v[18:19], 0, v[2:3]
	s_waitcnt lgkmcnt(0)
	s_barrier
	v_lshl_add_u64 v[8:9], v[22:23], 0, v[6:7]
	global_load_dwordx4 v[130:133], v[4:5], off
	global_load_dwordx4 v[134:137], v[8:9], off
	v_lshl_add_u64 v[4:5], v[18:19], 0, v[6:7]
	global_load_dwordx4 v[138:141], v[2:3], off
	global_load_dwordx4 v[142:145], v[4:5], off
	v_lshlrev_b32_e32 v3, 1, v181
	v_lshlrev_b32_e32 v2, 4, v181
	v_and_b32_e32 v3, 32, v3
	v_and_b32_e32 v4, 0xc0, v2
	v_and_or_b32 v3, v26, s5, v3
	v_and_b32_e32 v5, 0x70, v2
	v_bitop3_b32 v192, v0, v2, s78 bitop3:0x78
	v_bitop3_b32 v193, v0, v5, 32 bitop3:0x36
	v_bitop3_b32 v194, v0, v5, 64 bitop3:0x36
	v_bitop3_b32 v195, v0, v5, s4 bitop3:0x36
	v_cmp_gt_u32_e64 s[4:5], 32, v67
	v_add3_u32 v197, v4, s6, v3
	s_cbranch_scc1 .LBB0_687
; template <int KB, bool SK>
; __device__ __forceinline__ void qkt(f32x16& p0, f32x16& p1, const char* K_lds, int r32, int hi, const bf16x8* qr, bool act) {
;     ...
;     for (int dd = 0; dd < 4; ++dd) kb[dd] = K_lds + KB * SHM_K + KSWZ(r32, (dd * 16 + hi * 8) * 2);
; #pragma unroll
;     for (int d0 = 0; d0 < 8; ++d0) { const char* a = kb[d0 & 3] + (d0 >> 2) * 128;
;         bf16x8 b0 = *reinterpret_cast<const bf16x8*>(a);
;         bf16x8 b1 = *reinterpret_cast<const bf16x8*>(a + 32 * 256);
;         p0 = __builtin_amdgcn_mfma_f32_32x32x16_bf16(b0, qr[d0], p0, 0, 0, 0);
;         p1 = __builtin_amdgcn_mfma_f32_32x32x16_bf16(b1, qr[d0], p1, 0, 0, 0); }
; __device__ __forceinline__ void sb_block(const bf16* Qb, const bf16* Kh, const bf16* Vh, bf16* Ob, int q0, char* lds) {
;     ...
;             qkt<0, false>(p0, p1, K_lds + buf * SHM_K, r32, hi, qr, true);
;             const int dq = trow - kb - 4 * hi;
; #pragma unroll
;             for (int r = 0; r < 16; ++r) { const int c = (r & 3) + 8 * (r >> 2);
;                 const float z0 = p0[r], z1 = p1[r];
;                 const float a0 = -(fmaxf(z0, 0.f) + __builtin_amdgcn_logf(1.f + __builtin_amdgcn_exp2f(-fabsf(z0))));
;                 const float a1 = -(fmaxf(z1, 0.f) + __builtin_amdgcn_logf(1.f + __builtin_amdgcn_exp2f(-fabsf(z1))));
;                 l0[r] = (c < dq) ? a0 : 0.f; l1[r] = (c + 32 < dq) ? a1 : 0.f; }
	v_add3_u32 v0, 0, v192, v191
	ds_read_b128 v[2:5], v0 offset:32768
	ds_read_b128 v[6:9], v0 offset:40960
	v_add3_u32 v42, 0, v193, v191
	ds_read_b128 v[34:37], v42 offset:32768
	ds_read_b128 v[38:41], v42 offset:40960
	v_add3_u32 v43, 0, v194, v191
	s_waitcnt vmcnt(5) lgkmcnt(3)
	v_mfma_f32_32x32x16_bf16 v[18:33], v[2:5], v[122:125], 0
	v_add3_u32 v44, 0, v195, v191
	s_waitcnt lgkmcnt(2)
	v_mfma_f32_32x32x16_bf16 v[2:17], v[6:9], v[122:125], 0
	s_waitcnt lgkmcnt(1)
	v_mfma_f32_32x32x16_bf16 v[18:33], v[34:37], v[98:101], v[18:33]
	s_waitcnt lgkmcnt(0)
	v_mfma_f32_32x32x16_bf16 v[2:17], v[38:41], v[98:101], v[2:17]
	ds_read_b128 v[34:37], v43 offset:32768
	ds_read_b128 v[38:41], v43 offset:40960
	s_waitcnt lgkmcnt(1)
	v_mfma_f32_32x32x16_bf16 v[18:33], v[34:37], v[102:105], v[18:33]
	s_waitcnt lgkmcnt(0)
	v_mfma_f32_32x32x16_bf16 v[2:17], v[38:41], v[102:105], v[2:17]
	ds_read_b128 v[34:37], v44 offset:32768
	ds_read_b128 v[38:41], v44 offset:40960
	s_waitcnt lgkmcnt(1)
	v_mfma_f32_32x32x16_bf16 v[18:33], v[34:37], v[106:109], v[18:33]
	s_waitcnt lgkmcnt(0)
	v_mfma_f32_32x32x16_bf16 v[2:17], v[38:41], v[106:109], v[2:17]
	ds_read_b128 v[34:37], v0 offset:32896
	ds_read_b128 v[38:41], v0 offset:41088
	v_or_b32_e32 v0, s10, v196
	v_sub_u32_e32 v0, v190, v0
	v_cmp_lt_i32_e64 s[6:7], 32, v0
	v_cmp_lt_i32_e64 s[10:11], 33, v0
	v_cmp_lt_i32_e64 s[8:9], 1, v0
	v_cmp_lt_i32_e64 s[14:15], 34, v0
	s_waitcnt lgkmcnt(1)
	v_mfma_f32_32x32x16_bf16 v[18:33], v[34:37], v[110:113], v[18:33]
	v_cmp_lt_i32_e64 s[12:13], 2, v0
	v_cmp_lt_i32_e64 s[22:23], 35, v0
	v_cmp_lt_i32_e64 s[20:21], 3, v0
	v_cmp_lt_i32_e64 s[18:19], 40, v0
	v_cmp_lt_i32_e64 s[16:17], 8, v0
	v_cmp_lt_i32_e64 s[26:27], 41, v0
	v_cmp_lt_i32_e64 s[24:25], 9, v0
	s_waitcnt lgkmcnt(0)
	v_mfma_f32_32x32x16_bf16 v[2:17], v[38:41], v[110:113], v[2:17]
	ds_read_b128 v[34:37], v42 offset:32896
	ds_read_b128 v[38:41], v42 offset:41088
	v_cmp_lt_i32_e64 s[30:31], 42, v0
	v_cmp_lt_i32_e64 s[28:29], 10, v0
	v_cmp_lt_i32_e64 s[40:41], 43, v0
	v_cmp_lt_i32_e64 s[38:39], 11, v0
	v_cmp_lt_i32_e64 s[36:37], 48, v0
	v_cmp_lt_i32_e64 s[34:35], 16, v0
	s_waitcnt lgkmcnt(1)
	v_mfma_f32_32x32x16_bf16 v[18:33], v[34:37], v[114:117], v[18:33]
	v_cmp_lt_i32_e64 s[44:45], 49, v0
	v_cmp_lt_i32_e64 s[42:43], 17, v0
	v_cmp_lt_i32_e64 s[48:49], 50, v0
	v_cmp_lt_i32_e64 s[46:47], 18, v0
	v_cmp_lt_i32_e64 s[56:57], 51, v0
	v_cmp_lt_i32_e64 s[54:55], 19, v0
	v_cmp_lt_i32_e64 s[52:53], 56, v0
	s_waitcnt lgkmcnt(0)
	v_mfma_f32_32x32x16_bf16 v[2:17], v[38:41], v[114:117], v[2:17]
	ds_read_b128 v[34:37], v43 offset:32896
	ds_read_b128 v[38:41], v43 offset:41088
	v_cmp_lt_i32_e64 s[50:51], 24, v0
	v_cmp_lt_i32_e64 s[60:61], 57, v0
	v_cmp_lt_i32_e64 s[58:59], 25, v0
	v_cmp_lt_i32_e64 s[64:65], 58, v0
	v_cmp_lt_i32_e64 s[62:63], 26, v0
	v_cmp_lt_i32_e64 s[66:67], 27, v0
	s_waitcnt lgkmcnt(1)
	v_mfma_f32_32x32x16_bf16 v[18:33], v[34:37], v[118:121], v[18:33]
	v_cmp_lt_i32_e32 vcc, 0, v0
	v_cmp_lt_i32_e64 s[68:69], 59, v0
	s_waitcnt lgkmcnt(0)
	v_mfma_f32_32x32x16_bf16 v[2:17], v[38:41], v[118:121], v[2:17]
	ds_read_b128 v[34:37], v44 offset:32896
	ds_read_b128 v[38:41], v44 offset:41088
	s_waitcnt vmcnt(4) lgkmcnt(1)
	v_mfma_f32_32x32x16_bf16 v[18:33], v[34:37], v[126:129], v[18:33]
	s_waitcnt lgkmcnt(0)
	v_mfma_f32_32x32x16_bf16 v[2:17], v[38:41], v[126:129], v[2:17]
	s_nop 9
	v_exp_f32_e64 v35, -|v18|
	v_max_f32_e32 v34, 0, v18
	v_add_f32_e32 v35, 1.0, v35
	v_log_f32_e32 v35, v35
	v_exp_f32_e64 v36, -|v2|
	v_exp_f32_e64 v37, -|v3|
	v_add_f32_e32 v34, v34, v35
	v_add_f32_e32 v36, 1.0, v36
	v_log_f32_e32 v36, v36
	v_max_f32_e32 v35, 0, v2
	v_add_f32_e32 v37, 1.0, v37
	v_log_f32_e32 v37, v37
	v_add_f32_e32 v35, v35, v36
	v_exp_f32_e64 v36, -|v19|
	v_cndmask_b32_e64 v56, 0, -v35, s[6:7]
	v_max_f32_e32 v35, 0, v19
	v_add_f32_e32 v36, 1.0, v36
	v_log_f32_e32 v36, v36
	v_exp_f32_e64 v38, -|v4|
	v_exp_f32_e64 v39, -|v5|
	v_cndmask_b32_e64 v34, 0, -v34, vcc
	v_add_f32_e32 v35, v35, v36
	v_max_f32_e32 v36, 0, v3
	v_add_f32_e32 v37, v36, v37
	v_cndmask_b32_e64 v57, 0, -v37, s[10:11]
	v_exp_f32_e64 v37, -|v20|
	v_add_f32_e32 v38, 1.0, v38
	v_cndmask_b32_e64 v36, 0, -v35, s[8:9]
	v_add_f32_e32 v37, 1.0, v37
	v_log_f32_e32 v37, v37
	v_log_f32_e32 v38, v38
	v_max_f32_e32 v35, 0, v20
	v_add_f32_e32 v39, 1.0, v39
	v_add_f32_e32 v35, v35, v37
	v_max_f32_e32 v37, 0, v4
	v_add_f32_e32 v37, v37, v38
	v_cndmask_b32_e64 v58, 0, -v37, s[14:15]
	v_exp_f32_e64 v37, -|v21|
	v_cndmask_b32_e64 v38, 0, -v35, s[12:13]
	v_log_f32_e32 v39, v39
	v_add_f32_e32 v37, 1.0, v37
	v_log_f32_e32 v37, v37
	v_max_f32_e32 v35, 0, v21
	v_add_f32_e32 v0, v56, v57
	v_add_f32_e32 v35, v35, v37
	v_max_f32_e32 v37, 0, v5
	v_add_f32_e32 v37, v37, v39
	v_cndmask_b32_e64 v61, 0, -v37, s[22:23]
	v_exp_f32_e64 v37, -|v22|
	v_exp_f32_e64 v39, -|v6|
	v_cndmask_b32_e64 v40, 0, -v35, s[20:21]
	v_add_f32_e32 v37, 1.0, v37
	v_log_f32_e32 v37, v37
	v_add_f32_e32 v39, 1.0, v39
	v_log_f32_e32 v39, v39
	v_max_f32_e32 v35, 0, v22
	v_add_f32_e32 v35, v35, v37
	v_max_f32_e32 v37, 0, v6
	v_add_f32_e32 v37, v37, v39
	v_cndmask_b32_e64 v60, 0, -v37, s[18:19]
	v_exp_f32_e64 v37, -|v23|
	v_exp_f32_e64 v39, -|v7|
	v_cndmask_b32_e64 v59, 0, -v35, s[16:17]
	v_add_f32_e32 v37, 1.0, v37
	v_log_f32_e32 v37, v37
	v_add_f32_e32 v39, 1.0, v39
	v_log_f32_e32 v39, v39
	v_max_f32_e32 v35, 0, v23
	v_add_f32_e32 v35, v35, v37
	v_max_f32_e32 v37, 0, v7
	v_add_f32_e32 v37, v37, v39
	v_cndmask_b32_e64 v63, 0, -v37, s[26:27]
	v_exp_f32_e64 v37, -|v24|
	v_exp_f32_e64 v39, -|v8|
	v_cndmask_b32_e64 v62, 0, -v35, s[24:25]
	v_add_f32_e32 v37, 1.0, v37
	v_log_f32_e32 v37, v37
	v_add_f32_e32 v39, 1.0, v39
	v_log_f32_e32 v39, v39
; __device__ __forceinline__ void sb_block(const bf16* Qb, const bf16* Kh, const bf16* Vh, bf16* Ob, int q0, char* lds) {
;     ...
;                 const float a0 = -(fmaxf(z0, 0.f) + __builtin_amdgcn_logf(1.f + __builtin_amdgcn_exp2f(-fabsf(z0))));
;                 const float a1 = -(fmaxf(z1, 0.f) + __builtin_amdgcn_logf(1.f + __builtin_amdgcn_exp2f(-fabsf(z1))));
;                 l0[r] = (c < dq) ? a0 : 0.f; l1[r] = (c + 32 < dq) ? a1 : 0.f; }
;             float gs[8], ot[8], E[8];
; #pragma unroll
;             for (int k = 0; k < 4; ++k) { gs[k] = (l0[4 * k] + l0[4 * k + 1]) + (l0[4 * k + 2] + l0[4 * k + 3]); gs[4 + k] = (l1[4 * k] + l1[4 * k + 1]) + (l1[4 * k + 2] + l1[4 * k + 3]); }
; #pragma unroll
;             for (int k = 0; k < 8; ++k) { const unsigned gu = __float_as_uint(gs[k]); auto rr = __builtin_amdgcn_permlane32_swap(gu, gu, false, false); ot[k] = __uint_as_float(hi ? rr[0] : rr[1]); }
;             float acc = 0.f;
; #pragma unroll
;             for (int k = 7; k >= 0; --k) { E[k] = acc + (hi == 0 ? ot[k] : 0.f); acc += gs[k] + ot[k]; }
	v_max_f32_e32 v35, 0, v24
	v_add_f32_e32 v35, v35, v37
	v_max_f32_e32 v37, 0, v8
	v_add_f32_e32 v37, v37, v39
	v_cndmask_b32_e64 v65, 0, -v37, s[30:31]
	v_exp_f32_e64 v37, -|v25|
	v_exp_f32_e64 v39, -|v9|
	v_cndmask_b32_e64 v64, 0, -v35, s[28:29]
	v_add_f32_e32 v37, 1.0, v37
	v_log_f32_e32 v37, v37
	v_add_f32_e32 v39, 1.0, v39
	v_log_f32_e32 v39, v39
	v_max_f32_e32 v35, 0, v25
	v_add_f32_e32 v35, v35, v37
	v_max_f32_e32 v37, 0, v9
	v_add_f32_e32 v37, v37, v39
	v_cndmask_b32_e64 v70, 0, -v37, s[40:41]
	v_exp_f32_e64 v37, -|v26|
	v_exp_f32_e64 v39, -|v10|
	v_cndmask_b32_e64 v69, 0, -v35, s[38:39]
	v_add_f32_e32 v37, 1.0, v37
	v_log_f32_e32 v37, v37
	v_add_f32_e32 v39, 1.0, v39
	v_log_f32_e32 v39, v39
	v_max_f32_e32 v35, 0, v26
	v_add_f32_e32 v35, v35, v37
	v_max_f32_e32 v37, 0, v10
	v_add_f32_e32 v37, v37, v39
	v_cndmask_b32_e64 v42, 0, -v37, s[36:37]
	v_exp_f32_e64 v37, -|v27|
	v_exp_f32_e64 v39, -|v11|
	v_cndmask_b32_e64 v68, 0, -v35, s[34:35]
	v_add_f32_e32 v37, 1.0, v37
	v_log_f32_e32 v37, v37
	v_add_f32_e32 v39, 1.0, v39
	v_log_f32_e32 v39, v39
	v_max_f32_e32 v35, 0, v27
	v_add_f32_e32 v35, v35, v37
	v_max_f32_e32 v37, 0, v11
	v_add_f32_e32 v37, v37, v39
	v_cndmask_b32_e64 v44, 0, -v37, s[44:45]
	v_exp_f32_e64 v37, -|v28|
	v_exp_f32_e64 v39, -|v12|
	v_cndmask_b32_e64 v71, 0, -v35, s[42:43]
	v_add_f32_e32 v37, 1.0, v37
	v_log_f32_e32 v37, v37
	v_add_f32_e32 v39, 1.0, v39
	v_log_f32_e32 v39, v39
	v_max_f32_e32 v35, 0, v28
	v_add_f32_e32 v35, v35, v37
	v_max_f32_e32 v37, 0, v12
	v_add_f32_e32 v37, v37, v39
	v_cndmask_b32_e64 v73, 0, -v37, s[48:49]
	v_exp_f32_e64 v37, -|v29|
	v_exp_f32_e64 v39, -|v13|
	v_cndmask_b32_e64 v72, 0, -v35, s[46:47]
	v_add_f32_e32 v37, 1.0, v37
	v_log_f32_e32 v37, v37
	v_add_f32_e32 v39, 1.0, v39
	v_log_f32_e32 v39, v39
	v_max_f32_e32 v35, 0, v29
	v_add_f32_e32 v35, v35, v37
	v_max_f32_e32 v37, 0, v13
	v_add_f32_e32 v37, v37, v39
	v_cndmask_b32_e64 v76, 0, -v37, s[56:57]
	v_exp_f32_e64 v37, -|v30|
	v_exp_f32_e64 v39, -|v14|
	v_cndmask_b32_e64 v75, 0, -v35, s[54:55]
	v_add_f32_e32 v37, 1.0, v37
	v_log_f32_e32 v37, v37
	v_add_f32_e32 v39, 1.0, v39
	v_log_f32_e32 v39, v39
	v_max_f32_e32 v35, 0, v30
	v_add_f32_e32 v35, v35, v37
	v_max_f32_e32 v37, 0, v14
	v_add_f32_e32 v37, v37, v39
	v_cndmask_b32_e64 v74, 0, -v37, s[52:53]
	v_exp_f32_e64 v37, -|v31|
	v_exp_f32_e64 v39, -|v15|
	v_cndmask_b32_e64 v46, 0, -v35, s[50:51]
	v_add_f32_e32 v37, 1.0, v37
	v_log_f32_e32 v37, v37
	v_add_f32_e32 v39, 1.0, v39
	v_log_f32_e32 v39, v39
	v_max_f32_e32 v35, 0, v31
	v_add_f32_e32 v35, v35, v37
	v_max_f32_e32 v37, 0, v15
	v_add_f32_e32 v37, v37, v39
	v_cndmask_b32_e64 v77, 0, -v37, s[60:61]
	v_exp_f32_e64 v37, -|v32|
	v_exp_f32_e64 v39, -|v16|
	v_cndmask_b32_e64 v48, 0, -v35, s[58:59]
	v_add_f32_e32 v37, 1.0, v37
	v_log_f32_e32 v37, v37
	v_add_f32_e32 v39, 1.0, v39
	v_log_f32_e32 v39, v39
	v_max_f32_e32 v35, 0, v32
	v_add_f32_e32 v35, v35, v37
	v_max_f32_e32 v37, 0, v16
	v_add_f32_e32 v37, v37, v39
	v_cndmask_b32_e64 v80, 0, -v37, s[64:65]
	v_exp_f32_e64 v37, -|v33|
	v_exp_f32_e64 v39, -|v17|
	v_cndmask_b32_e64 v50, 0, -v35, s[62:63]
	v_add_f32_e32 v37, 1.0, v37
	v_log_f32_e32 v37, v37
	v_add_f32_e32 v39, 1.0, v39
	v_log_f32_e32 v39, v39
	v_max_f32_e32 v35, 0, v33
	v_add_f32_e32 v35, v35, v37
	v_max_f32_e32 v37, 0, v17
	v_cndmask_b32_e64 v52, 0, -v35, s[66:67]
	v_add_f32_e32 v35, v58, v61
	v_add_f32_e32 v37, v37, v39
	v_add_f32_e32 v47, v0, v35
	v_add_f32_e32 v0, v59, v62
	v_add_f32_e32 v35, v64, v69
	v_cndmask_b32_e64 v81, 0, -v37, s[68:69]
	v_add_f32_e32 v35, v0, v35
	v_add_f32_e32 v0, v60, v63
	v_add_f32_e32 v37, v65, v70
	v_add_f32_e32 v39, v0, v37
	v_add_f32_e32 v0, v68, v71
	v_add_f32_e32 v37, v72, v75
	v_add_f32_e32 v82, v0, v37
	v_mov_b32_e32 v0, v35
	v_mov_b32_e32 v37, v35
	s_nop 1
	v_permlane32_swap_b32_e32 v0, v37
	v_cndmask_b32_e64 v37, v0, v37, s[4:5]
	v_mov_b32_e32 v0, v82
	v_mov_b32_e32 v41, v82
	s_nop 1
	v_permlane32_swap_b32_e32 v0, v41
	v_cndmask_b32_e64 v83, v0, v41, s[4:5]
	v_mov_b32_e32 v0, v47
	v_mov_b32_e32 v41, v47
	s_nop 1
	v_permlane32_swap_b32_e32 v0, v41
	v_add_f32_e32 v43, v74, v77
	v_add_f32_e32 v45, v80, v81
	v_cndmask_b32_e64 v49, v0, v41, s[4:5]
	v_mov_b32_e32 v0, v39
	v_mov_b32_e32 v41, v39
	s_nop 1
	v_permlane32_swap_b32_e32 v0, v41
	v_pk_add_f32 v[78:79], v[42:43], v[44:45]
	v_cndmask_b32_e64 v41, v0, v41, s[4:5]
	v_mov_b32_e32 v0, v79
	v_mov_b32_e32 v43, v79
	s_nop 1
	v_permlane32_swap_b32_e32 v0, v43
	v_add_f32_e32 v54, v73, v76
	v_cndmask_b32_e64 v55, v0, v43, s[4:5]
	v_pk_add_f32 v[78:79], v[78:79], v[54:55]
	v_add_f32_e32 v51, v39, v41
	v_mov_b32_e32 v0, v78
	v_mov_b32_e32 v43, v78
	s_nop 1
	v_permlane32_swap_b32_e32 v0, v43
	v_cndmask_b32_e64 v0, v0, v43, s[4:5]
	v_add_f32_e32 v43, 0, v55
	v_cndmask_b32_e64 v45, 0, v0, s[4:5]
	v_pk_add_f32 v[54:55], v[78:79], v[0:1]
	v_pk_add_f32 v[78:79], v[46:47], v[48:49]
	v_add_f32_e32 v0, v45, v55
	v_pk_add_f32 v[54:55], v[54:55], v[54:55] op_sel:[0,1] op_sel_hi:[1,0]
	v_cndmask_b32_e64 v45, 0, v41, s[4:5]
	v_mov_b32_e32 v53, v54
	v_add_f32_e32 v45, v45, v54
	v_pk_add_f32 v[54:55], v[50:51], v[52:53]
	v_cndmask_b32_e64 v39, 0, v49, s[4:5]
	v_pk_add_f32 v[78:79], v[78:79], v[54:55]
	v_cndmask_b32_e64 v53, 0, v37, s[4:5]
	v_mov_b32_e32 v41, v78
	v_mov_b32_e32 v47, v78
	s_nop 1
	v_permlane32_swap_b32_e32 v41, v47
	v_cndmask_b32_e64 v41, v41, v47, s[4:5]
	v_add_f32_e32 v47, v39, v55
	v_cndmask_b32_e64 v39, 0, v41, s[4:5]
	v_add_f32_e32 v49, v39, v79
	v_add_f32_e32 v39, v78, v41
	v_add_f32_e32 v41, v39, v79
	v_cndmask_b32_e64 v39, 0, v83, s[4:5]
	v_add_f32_e32 v51, v39, v41
	v_add_f32_e32 v39, v82, v83
	v_pk_add_f32 v[78:79], v[38:39], v[40:41]
; #define SBAR() __builtin_amdgcn_sched_barrier(0)
; __device__ __forceinline__ void sb_block(const bf16* Qb, const bf16* Kh, const bf16* Vh, bf16* Ob, int q0, char* lds) {
;     ...
;             for (int k = 7; k >= 0; --k) { E[k] = acc + (hi == 0 ? ot[k] : 0.f); acc += gs[k] + ot[k]; }
; #pragma unroll
;             for (int k = 0; k < 4; ++k) {
;                 float s0 = E[k] + R, s1 = E[4 + k] + R;
; #pragma unroll
;                 for (int q = 3; q >= 0; --q) { const int r = 4 * k + q, c = (r & 3) + 8 * (r >> 2);
;                     s0 += l0[r]; s1 += l1[r];
;                     const float w0 = __builtin_amdgcn_exp2f(p0[r] + s0), w1 = __builtin_amdgcn_exp2f(p1[r] + s1);
;                     p0[r] = (c < dq) ? w0 : 0.f; p1[r] = (c + 32 < dq) ? w1 : 0.f; }
;             }
;             R += acc;
;             bf16x8 pa0, pa1, pa2, pa3;
;     ...
;             PK4(p0, 0, pa0); PK4(p0, 8, pa1); PK4(p1, 0, pa2); PK4(p1, 8, pa3);
;     ...
;             SBAR();
;             pv_tile<0, false>(o, vb0 + buf * SHM_V, pa0, pa1, pa2, pa3, true);
	v_pk_add_f32 v[54:55], v[34:35], v[36:37]
	v_add_f32_e32 v0, v76, v0
	v_pk_add_f32 v[54:55], v[54:55], v[78:79]
	v_add_f32_e32 v13, v13, v0
	v_mov_b32_e32 v35, v54
	v_mov_b32_e32 v37, v54
	s_nop 1
	v_permlane32_swap_b32_e32 v35, v37
	v_cndmask_b32_e64 v35, v35, v37, s[4:5]
	v_cndmask_b32_e64 v39, 0, v35, s[4:5]
	v_add_f32_e32 v39, v39, v55
	v_add_f32_e32 v39, 0, v39
	v_add_f32_e32 v39, v40, v39
	v_add_f32_e32 v38, v38, v39
	v_add_f32_e32 v36, v36, v38
	v_add_f32_e32 v37, v53, v79
	v_add_f32_e32 v34, v34, v36
	v_add_f32_e32 v18, v18, v34
	v_add_f32_e32 v34, 0, v37
	v_add_f32_e32 v34, v69, v34
	v_add_f32_e32 v25, v25, v34
	v_add_f32_e32 v34, v64, v34
	v_add_f32_e32 v24, v24, v34
	v_add_f32_e32 v34, v62, v34
	v_add_f32_e32 v23, v23, v34
	v_add_f32_e32 v34, v59, v34
	v_add_f32_e32 v22, v22, v34
	v_add_f32_e32 v34, v75, v51
	v_add_f32_e32 v29, v29, v34
	v_add_f32_e32 v34, v72, v34
	v_add_f32_e32 v28, v28, v34
	v_add_f32_e32 v34, v71, v34
	v_add_f32_e32 v27, v27, v34
	v_add_f32_e32 v34, v68, v34
	v_add_f32_e32 v26, v26, v34
	v_add_f32_e32 v40, v61, v47
	v_exp_f32_e32 v26, v26
	v_add_f32_e32 v21, v21, v39
	v_add_f32_e32 v39, v58, v40
	v_add_f32_e32 v0, v73, v0
	v_add_f32_e32 v20, v20, v38
	v_add_f32_e32 v38, v57, v39
	v_add_f32_e32 v12, v12, v0
	v_add_f32_e32 v0, v44, v0
	v_cndmask_b32_e64 v43, 0, v43, s[4:5]
	v_add_f32_e32 v19, v19, v36
	v_add_f32_e32 v36, v56, v38
	v_add_f32_e32 v11, v11, v0
	v_add_f32_e32 v0, v42, v0
	v_add_f32_e32 v2, v2, v36
	v_add_f32_e32 v36, v70, v45
	v_add_f32_e32 v0, v10, v0
	v_cndmask_b32_e64 v10, 0, v26, s[34:35]
	v_add_f32_e32 v26, v52, v49
	v_add_f32_e32 v34, v81, v43
	v_add_f32_e32 v9, v9, v36
	v_add_f32_e32 v36, v65, v36
	v_add_f32_e32 v33, v33, v26
	v_add_f32_e32 v17, v17, v34
	v_add_f32_e32 v26, v50, v26
	v_add_f32_e32 v34, v80, v34
	v_add_f32_e32 v8, v8, v36
	v_add_f32_e32 v36, v63, v36
	v_add_f32_e32 v32, v32, v26
	v_add_f32_e32 v16, v16, v34
	v_add_f32_e32 v26, v48, v26
	v_add_f32_e32 v34, v77, v34
	v_add_f32_e32 v7, v7, v36
	v_add_f32_e32 v36, v60, v36
	v_add_f32_e32 v31, v31, v26
	v_add_f32_e32 v15, v15, v34
	v_add_f32_e32 v26, v46, v26
	v_add_f32_e32 v34, v74, v34
	v_exp_f32_e32 v21, v21
	v_add_f32_e32 v5, v5, v40
	v_exp_f32_e32 v20, v20
	v_add_f32_e32 v4, v4, v39
	v_exp_f32_e32 v19, v19
	v_add_f32_e32 v3, v3, v38
	v_exp_f32_e32 v18, v18
	v_exp_f32_e32 v25, v25
	v_exp_f32_e32 v24, v24
	v_exp_f32_e32 v23, v23
	v_exp_f32_e32 v22, v22
	v_add_f32_e32 v6, v6, v36
	v_add_f32_e32 v26, v30, v26
	v_add_f32_e32 v14, v14, v34
	v_exp_f32_e32 v5, v5
	v_exp_f32_e32 v4, v4
	v_exp_f32_e32 v3, v3
	v_exp_f32_e32 v2, v2
	v_exp_f32_e32 v9, v9
	v_exp_f32_e32 v8, v8
	v_exp_f32_e32 v7, v7
	v_exp_f32_e32 v6, v6
	v_exp_f32_e32 v29, v29
	v_exp_f32_e32 v13, v13
	v_exp_f32_e32 v28, v28
	v_exp_f32_e32 v12, v12
	v_exp_f32_e32 v27, v27
	v_exp_f32_e32 v11, v11
	v_exp_f32_e32 v0, v0
	v_exp_f32_e32 v33, v33
	v_exp_f32_e32 v17, v17
	v_exp_f32_e32 v32, v32
	v_exp_f32_e32 v16, v16
	v_exp_f32_e32 v31, v31
	v_exp_f32_e32 v15, v15
	v_exp_f32_e32 v26, v26
	v_exp_f32_e32 v14, v14
	v_add_f32_e32 v35, v54, v35
	v_cndmask_b32_e64 v21, 0, v21, s[20:21]
	v_cndmask_b32_e64 v20, 0, v20, s[12:13]
	v_cndmask_b32_e64 v19, 0, v19, s[8:9]
	v_cndmask_b32_e32 v18, 0, v18, vcc
	v_cndmask_b32_e64 v25, 0, v25, s[38:39]
	v_cndmask_b32_e64 v24, 0, v24, s[28:29]
	v_cndmask_b32_e64 v23, 0, v23, s[24:25]
	v_cndmask_b32_e64 v22, 0, v22, s[16:17]
	v_cndmask_b32_e64 v5, 0, v5, s[22:23]
	v_cndmask_b32_e64 v4, 0, v4, s[14:15]
	v_cndmask_b32_e64 v3, 0, v3, s[10:11]
	v_cndmask_b32_e64 v2, 0, v2, s[6:7]
	v_cndmask_b32_e64 v9, 0, v9, s[40:41]
	v_cndmask_b32_e64 v8, 0, v8, s[30:31]
	v_cndmask_b32_e64 v7, 0, v7, s[26:27]
	v_cndmask_b32_e64 v6, 0, v6, s[18:19]
	v_cndmask_b32_e64 v29, 0, v29, s[54:55]
	v_cndmask_b32_e64 v13, 0, v13, s[56:57]
	v_cndmask_b32_e64 v28, 0, v28, s[46:47]
	v_cndmask_b32_e64 v12, 0, v12, s[48:49]
	v_cndmask_b32_e64 v27, 0, v27, s[42:43]
	v_cndmask_b32_e64 v11, 0, v11, s[44:45]
	v_cndmask_b32_e64 v0, 0, v0, s[36:37]
	v_cndmask_b32_e64 v33, 0, v33, s[66:67]
	v_cndmask_b32_e64 v17, 0, v17, s[68:69]
	v_cndmask_b32_e64 v32, 0, v32, s[62:63]
	v_cndmask_b32_e64 v16, 0, v16, s[64:65]
	v_cndmask_b32_e64 v31, 0, v31, s[58:59]
	v_cndmask_b32_e64 v15, 0, v15, s[60:61]
	v_cndmask_b32_e64 v26, 0, v26, s[50:51]
	v_cndmask_b32_e64 v14, 0, v14, s[52:53]
	v_add_f32_e32 v92, v35, v55
	v_cvt_pk_bf16_f32 v50, v18, v19
	v_cvt_pk_bf16_f32 v51, v20, v21
	v_cvt_pk_bf16_f32 v52, v22, v23
	v_cvt_pk_bf16_f32 v53, v24, v25
	v_add_f32_e32 v198, 0, v92
	v_permlane32_swap_b32_e32 v50, v52
	v_permlane32_swap_b32_e32 v51, v53
	v_cvt_pk_bf16_f32 v68, v10, v27
	v_cvt_pk_bf16_f32 v69, v28, v29
	v_cvt_pk_bf16_f32 v70, v26, v31
	v_cvt_pk_bf16_f32 v71, v32, v33
	v_cvt_pk_bf16_f32 v72, v2, v3
	v_cvt_pk_bf16_f32 v73, v4, v5
	v_cvt_pk_bf16_f32 v74, v6, v7
	v_cvt_pk_bf16_f32 v75, v8, v9
	v_cvt_pk_bf16_f32 v76, v0, v11
	v_cvt_pk_bf16_f32 v77, v12, v13
	v_cvt_pk_bf16_f32 v78, v14, v15
	v_cvt_pk_bf16_f32 v79, v16, v17
	v_permlane32_swap_b32_e32 v68, v70
	v_permlane32_swap_b32_e32 v69, v71
	v_permlane32_swap_b32_e32 v72, v74
	v_permlane32_swap_b32_e32 v73, v75
	v_permlane32_swap_b32_e32 v76, v78
	v_permlane32_swap_b32_e32 v77, v79
	ds_read_b64_tr_b16 v[2:3], v197 offset:0
	ds_read_b64_tr_b16 v[4:5], v197 offset:0x800
	ds_read_b64_tr_b16 v[18:19], v197 offset:0x1000
	ds_read_b64_tr_b16 v[20:21], v197 offset:0x1800
	ds_read_b64_tr_b16 v[22:23], v197 offset:0x2000
	ds_read_b64_tr_b16 v[24:25], v197 offset:0x2800
	ds_read_b64_tr_b16 v[26:27], v197 offset:0x3000
	ds_read_b64_tr_b16 v[28:29], v197 offset:0x3800
	s_waitcnt lgkmcnt(0)
; template <int VB, bool SK>
; __device__ __forceinline__ void pv_tile(f32x16* o, int vb0, bf16x8 pa0, bf16x8 pa1, bf16x8 pa2, bf16x8 pa3, bool act) {
;     ...
;     PV_D0(0); PV_D0(1); PV_D0(2); PV_D0(3);
; __device__ __forceinline__ void sb_block(const bf16* Qb, const bf16* Kh, const bf16* Vh, bf16* Ob, int q0, char* lds) {
;     ...
;             wdone = __all(R < SB_STOP);
	s_nop 0
	v_mfma_f32_32x32x16_bf16 v[2:17], v[50:53], v[2:5], 0
	v_mfma_f32_32x32x16_bf16 v[2:17], v[68:71], v[18:21], v[2:17]
	ds_read_b64_tr_b16 v[18:19], v197 offset:0x200
	ds_read_b64_tr_b16 v[20:21], v197 offset:0xa00
	ds_read_b64_tr_b16 v[34:35], v197 offset:0x1200
	ds_read_b64_tr_b16 v[36:37], v197 offset:0x1a00
	ds_read_b64_tr_b16 v[38:39], v197 offset:0x2200
	ds_read_b64_tr_b16 v[40:41], v197 offset:0x2a00
	ds_read_b64_tr_b16 v[42:43], v197 offset:0x3200
	v_mfma_f32_32x32x16_bf16 v[2:17], v[72:75], v[22:25], v[2:17]
	ds_read_b64_tr_b16 v[44:45], v197 offset:0x3a00
	s_waitcnt lgkmcnt(0)
	v_mfma_f32_32x32x16_bf16 v[2:17], v[76:79], v[26:29], v[2:17]
	v_mfma_f32_32x32x16_bf16 v[18:33], v[50:53], v[18:21], 0
	v_mfma_f32_32x32x16_bf16 v[18:33], v[68:71], v[34:37], v[18:33]
	ds_read_b64_tr_b16 v[34:35], v197 offset:0x400
	ds_read_b64_tr_b16 v[36:37], v197 offset:0xc00
	ds_read_b64_tr_b16 v[54:55], v197 offset:0x1400
	ds_read_b64_tr_b16 v[56:57], v197 offset:0x1c00
	ds_read_b64_tr_b16 v[58:59], v197 offset:0x2400
	ds_read_b64_tr_b16 v[60:61], v197 offset:0x2c00
	ds_read_b64_tr_b16 v[62:63], v197 offset:0x3400
	v_mfma_f32_32x32x16_bf16 v[18:33], v[72:75], v[38:41], v[18:33]
	ds_read_b64_tr_b16 v[64:65], v197 offset:0x3c00
	s_waitcnt lgkmcnt(0)
	v_mfma_f32_32x32x16_bf16 v[18:33], v[76:79], v[42:45], v[18:33]
	v_mfma_f32_32x32x16_bf16 v[34:49], v[50:53], v[34:37], 0
	v_mfma_f32_32x32x16_bf16 v[34:49], v[68:71], v[54:57], v[34:49]
	ds_read_b64_tr_b16 v[54:55], v197 offset:0x600
	ds_read_b64_tr_b16 v[56:57], v197 offset:0xe00
	ds_read_b64_tr_b16 v[80:81], v197 offset:0x1600
	ds_read_b64_tr_b16 v[82:83], v197 offset:0x1e00
	ds_read_b64_tr_b16 v[84:85], v197 offset:0x2600
	ds_read_b64_tr_b16 v[86:87], v197 offset:0x2e00
	ds_read_b64_tr_b16 v[88:89], v197 offset:0x3600
	v_mfma_f32_32x32x16_bf16 v[34:49], v[72:75], v[58:61], v[34:49]
	ds_read_b64_tr_b16 v[90:91], v197 offset:0x3e00
	s_waitcnt lgkmcnt(0)
	v_mfma_f32_32x32x16_bf16 v[34:49], v[76:79], v[62:65], v[34:49]
	v_mfma_f32_32x32x16_bf16 v[50:65], v[50:53], v[54:57], 0
	v_cmp_gt_f32_e32 vcc, s79, v92
	s_cmp_eq_u64 vcc, exec
	s_cselect_b64 s[8:9], -1, 0
	v_mfma_f32_32x32x16_bf16 v[50:65], v[68:71], v[80:83], v[50:65]
	v_mfma_f32_32x32x16_bf16 v[50:65], v[72:75], v[84:87], v[50:65]
	v_mfma_f32_32x32x16_bf16 v[50:65], v[76:79], v[88:91], v[50:65]
	s_branch .LBB0_688

; template <int KB, bool SK>
; __device__ __forceinline__ void qkt(f32x16& p0, f32x16& p1, const char* K_lds, int r32, int hi, const bf16x8* qr, bool act) {
;     ...
;     for (int dd = 0; dd < 4; ++dd) kb[dd] = K_lds + KB * SHM_K + KSWZ(r32, (dd * 16 + hi * 8) * 2);
; #pragma unroll
;     for (int d0 = 0; d0 < 8; ++d0) { const char* a = kb[d0 & 3] + (d0 >> 2) * 128;
;         bf16x8 b0 = *reinterpret_cast<const bf16x8*>(a);
;         bf16x8 b1 = *reinterpret_cast<const bf16x8*>(a + 32 * 256);
;         p0 = __builtin_amdgcn_mfma_f32_32x32x16_bf16(b0, qr[d0], p0, 0, 0, 0);
;         p1 = __builtin_amdgcn_mfma_f32_32x32x16_bf16(b1, qr[d0], p1, 0, 0, 0); }
; __device__ __forceinline__ void sb_block(const bf16* Qb, const bf16* Kh, const bf16* Vh, bf16* Ob, int q0, char* lds) {
;     ...
;             qkt<0, false>(p0, p1, K_lds + buf * SHM_K, r32, hi, qr, true);
;             const int dq = trow - kb - 4 * hi;
; #pragma unroll
;             for (int r = 0; r < 16; ++r) { const int c = (r & 3) + 8 * (r >> 2);
;                 const float z0 = p0[r], z1 = p1[r];
;                 const float a0 = -(fmaxf(z0, 0.f) + __builtin_amdgcn_logf(1.f + __builtin_amdgcn_exp2f(-fabsf(z0))));
;                 const float a1 = -(fmaxf(z1, 0.f) + __builtin_amdgcn_logf(1.f + __builtin_amdgcn_exp2f(-fabsf(z1))));
;                 l0[r] = (c < dq) ? a0 : 0.f; l1[r] = (c + 32 < dq) ? a1 : 0.f; }
.LBB0_700:
	v_add3_u32 v0, s12, v192, v191
	ds_read_b128 v[66:69], v0 offset:32768
	ds_read_b128 v[70:73], v0 offset:40960
	v_add3_u32 v162, s12, v193, v191
	ds_read_b128 v[154:157], v162 offset:32768
	ds_read_b128 v[158:161], v162 offset:40960
	v_add3_u32 v163, s12, v194, v191
	s_waitcnt lgkmcnt(3)
	v_mfma_f32_32x32x16_bf16 v[82:97], v[66:69], v[122:125], 0
	v_add3_u32 v164, s12, v195, v191
	s_waitcnt lgkmcnt(2)
	v_mfma_f32_32x32x16_bf16 v[66:81], v[70:73], v[122:125], 0
	s_waitcnt lgkmcnt(1)
	v_mfma_f32_32x32x16_bf16 v[82:97], v[154:157], v[98:101], v[82:97]
	s_waitcnt lgkmcnt(0)
	v_mfma_f32_32x32x16_bf16 v[66:81], v[158:161], v[98:101], v[66:81]
	ds_read_b128 v[154:157], v163 offset:32768
	ds_read_b128 v[158:161], v163 offset:40960
	s_waitcnt lgkmcnt(1)
	v_mfma_f32_32x32x16_bf16 v[82:97], v[154:157], v[102:105], v[82:97]
	s_waitcnt lgkmcnt(0)
	v_mfma_f32_32x32x16_bf16 v[66:81], v[158:161], v[102:105], v[66:81]
	ds_read_b128 v[154:157], v164 offset:32768
	ds_read_b128 v[158:161], v164 offset:40960
	s_waitcnt lgkmcnt(1)
	v_mfma_f32_32x32x16_bf16 v[82:97], v[154:157], v[106:109], v[82:97]
	s_waitcnt lgkmcnt(0)
	v_mfma_f32_32x32x16_bf16 v[66:81], v[158:161], v[106:109], v[66:81]
	ds_read_b128 v[154:157], v0 offset:32896
	ds_read_b128 v[158:161], v0 offset:41088
	v_or_b32_e32 v0, s97, v196
	v_sub_u32_e32 v0, v190, v0
	v_cmp_lt_i32_e64 s[8:9], 32, v0
	v_cmp_lt_i32_e64 s[12:13], 33, v0
	v_cmp_lt_i32_e64 s[10:11], 1, v0
	v_cmp_lt_i32_e64 s[16:17], 34, v0
	s_waitcnt lgkmcnt(1)
	v_mfma_f32_32x32x16_bf16 v[82:97], v[154:157], v[110:113], v[82:97]
	v_cmp_lt_i32_e64 s[14:15], 2, v0
	v_cmp_lt_i32_e64 s[24:25], 35, v0
	v_cmp_lt_i32_e64 s[22:23], 3, v0
	v_cmp_lt_i32_e64 s[20:21], 40, v0
	v_cmp_lt_i32_e64 s[18:19], 8, v0
	v_cmp_lt_i32_e64 s[28:29], 41, v0
	v_cmp_lt_i32_e64 s[26:27], 9, v0
	s_waitcnt lgkmcnt(0)
	v_mfma_f32_32x32x16_bf16 v[66:81], v[158:161], v[110:113], v[66:81]
	ds_read_b128 v[154:157], v162 offset:32896
	ds_read_b128 v[158:161], v162 offset:41088
	v_cmp_lt_i32_e64 s[34:35], 42, v0
	v_cmp_lt_i32_e64 s[30:31], 10, v0
	v_cmp_lt_i32_e64 s[42:43], 43, v0
	v_cmp_lt_i32_e64 s[40:41], 11, v0
	v_cmp_lt_i32_e64 s[38:39], 48, v0
	v_cmp_lt_i32_e64 s[36:37], 16, v0
	s_waitcnt lgkmcnt(1)
	v_mfma_f32_32x32x16_bf16 v[82:97], v[154:157], v[114:117], v[82:97]
	v_cmp_lt_i32_e64 s[46:47], 49, v0
	v_cmp_lt_i32_e64 s[44:45], 17, v0
	v_cmp_lt_i32_e64 s[50:51], 50, v0
	v_cmp_lt_i32_e64 s[48:49], 18, v0
	v_cmp_lt_i32_e64 s[58:59], 51, v0
	v_cmp_lt_i32_e64 s[56:57], 19, v0
	v_cmp_lt_i32_e64 s[54:55], 56, v0
	s_waitcnt lgkmcnt(0)
	v_mfma_f32_32x32x16_bf16 v[66:81], v[158:161], v[114:117], v[66:81]
	ds_read_b128 v[154:157], v163 offset:32896
	ds_read_b128 v[158:161], v163 offset:41088
	v_cmp_lt_i32_e64 s[52:53], 24, v0
	v_cmp_lt_i32_e64 s[62:63], 57, v0
	v_cmp_lt_i32_e64 s[60:61], 25, v0
	v_cmp_lt_i32_e64 s[66:67], 58, v0
	v_cmp_lt_i32_e64 s[64:65], 26, v0
	v_cmp_lt_i32_e64 s[68:69], 27, v0
	s_waitcnt lgkmcnt(1)
	v_mfma_f32_32x32x16_bf16 v[82:97], v[154:157], v[118:121], v[82:97]
	v_cmp_lt_i32_e32 vcc, 0, v0
	v_cmp_lt_i32_e64 s[70:71], 59, v0
	s_waitcnt lgkmcnt(0)
	v_mfma_f32_32x32x16_bf16 v[66:81], v[158:161], v[118:121], v[66:81]
	ds_read_b128 v[154:157], v164 offset:32896
	ds_read_b128 v[158:161], v164 offset:41088
	s_waitcnt lgkmcnt(1)
	v_mfma_f32_32x32x16_bf16 v[82:97], v[154:157], v[126:129], v[82:97]
	s_waitcnt lgkmcnt(0)
	v_mfma_f32_32x32x16_bf16 v[66:81], v[158:161], v[126:129], v[66:81]
	s_nop 9
	v_exp_f32_e64 v155, -|v82|
	v_max_f32_e32 v154, 0, v82
	v_add_f32_e32 v155, 1.0, v155
	v_log_f32_e32 v155, v155
	v_exp_f32_e64 v156, -|v66|
	v_exp_f32_e64 v157, -|v67|
	v_add_f32_e32 v154, v154, v155
	v_add_f32_e32 v156, 1.0, v156
	v_log_f32_e32 v156, v156
	v_max_f32_e32 v155, 0, v66
	v_add_f32_e32 v157, 1.0, v157
	v_log_f32_e32 v157, v157
	v_add_f32_e32 v155, v155, v156
	v_exp_f32_e64 v156, -|v83|
	v_cndmask_b32_e64 v199, 0, -v155, s[8:9]
	v_max_f32_e32 v155, 0, v83
	v_add_f32_e32 v156, 1.0, v156
	v_log_f32_e32 v156, v156
	v_exp_f32_e64 v158, -|v68|
	v_exp_f32_e64 v159, -|v69|
	v_cndmask_b32_e64 v154, 0, -v154, vcc
	v_add_f32_e32 v155, v155, v156
	v_max_f32_e32 v156, 0, v67
	v_add_f32_e32 v157, v156, v157
	v_cndmask_b32_e64 v200, 0, -v157, s[12:13]
	v_exp_f32_e64 v157, -|v84|
	v_add_f32_e32 v158, 1.0, v158
	v_cndmask_b32_e64 v156, 0, -v155, s[10:11]
	v_add_f32_e32 v157, 1.0, v157
	v_log_f32_e32 v157, v157
	v_log_f32_e32 v158, v158
	v_max_f32_e32 v155, 0, v84
	v_add_f32_e32 v159, 1.0, v159
	v_add_f32_e32 v155, v155, v157
	v_max_f32_e32 v157, 0, v68
	v_add_f32_e32 v157, v157, v158
	v_cndmask_b32_e64 v201, 0, -v157, s[16:17]
	v_exp_f32_e64 v157, -|v85|
	v_cndmask_b32_e64 v158, 0, -v155, s[14:15]
	v_log_f32_e32 v159, v159
	v_add_f32_e32 v157, 1.0, v157
	v_log_f32_e32 v157, v157
	v_max_f32_e32 v155, 0, v85
	v_add_f32_e32 v0, v199, v200
	v_add_f32_e32 v155, v155, v157
	v_max_f32_e32 v157, 0, v69
	v_add_f32_e32 v157, v157, v159
	v_cndmask_b32_e64 v204, 0, -v157, s[24:25]
	v_exp_f32_e64 v157, -|v86|
	v_exp_f32_e64 v159, -|v70|
	v_cndmask_b32_e64 v160, 0, -v155, s[22:23]
	v_add_f32_e32 v157, 1.0, v157
	v_log_f32_e32 v157, v157
	v_add_f32_e32 v159, 1.0, v159
	v_log_f32_e32 v159, v159
	v_max_f32_e32 v155, 0, v86
	v_add_f32_e32 v155, v155, v157
	v_max_f32_e32 v157, 0, v70
	v_add_f32_e32 v157, v157, v159
	v_cndmask_b32_e64 v203, 0, -v157, s[20:21]
	v_exp_f32_e64 v157, -|v87|
	v_exp_f32_e64 v159, -|v71|
	v_cndmask_b32_e64 v202, 0, -v155, s[18:19]
	v_add_f32_e32 v157, 1.0, v157
	v_log_f32_e32 v157, v157
	v_add_f32_e32 v159, 1.0, v159
	v_log_f32_e32 v159, v159
	v_max_f32_e32 v155, 0, v87
	v_add_f32_e32 v155, v155, v157
	v_max_f32_e32 v157, 0, v71
	v_add_f32_e32 v157, v157, v159
; __device__ __forceinline__ void sb_block(const bf16* Qb, const bf16* Kh, const bf16* Vh, bf16* Ob, int q0, char* lds) {
;     ...
;                 const float a0 = -(fmaxf(z0, 0.f) + __builtin_amdgcn_logf(1.f + __builtin_amdgcn_exp2f(-fabsf(z0))));
;                 const float a1 = -(fmaxf(z1, 0.f) + __builtin_amdgcn_logf(1.f + __builtin_amdgcn_exp2f(-fabsf(z1))));
;                 l0[r] = (c < dq) ? a0 : 0.f; l1[r] = (c + 32 < dq) ? a1 : 0.f; }
;             float gs[8], ot[8], E[8];
; #pragma unroll
;             for (int k = 0; k < 4; ++k) { gs[k] = (l0[4 * k] + l0[4 * k + 1]) + (l0[4 * k + 2] + l0[4 * k + 3]); gs[4 + k] = (l1[4 * k] + l1[4 * k + 1]) + (l1[4 * k + 2] + l1[4 * k + 3]); }
; #pragma unroll
;             for (int k = 0; k < 8; ++k) { const unsigned gu = __float_as_uint(gs[k]); auto rr = __builtin_amdgcn_permlane32_swap(gu, gu, false, false); ot[k] = __uint_as_float(hi ? rr[0] : rr[1]); }
;             float acc = 0.f;
; #pragma unroll
;             for (int k = 7; k >= 0; --k) { E[k] = acc + (hi == 0 ? ot[k] : 0.f); acc += gs[k] + ot[k]; }
	v_cndmask_b32_e64 v206, 0, -v157, s[28:29]
	v_exp_f32_e64 v157, -|v88|
	v_exp_f32_e64 v159, -|v72|
	v_cndmask_b32_e64 v205, 0, -v155, s[26:27]
	v_add_f32_e32 v157, 1.0, v157
	v_log_f32_e32 v157, v157
	v_add_f32_e32 v159, 1.0, v159
	v_log_f32_e32 v159, v159
	v_max_f32_e32 v155, 0, v88
	v_add_f32_e32 v155, v155, v157
	v_max_f32_e32 v157, 0, v72
	v_add_f32_e32 v157, v157, v159
	v_cndmask_b32_e64 v208, 0, -v157, s[34:35]
	v_exp_f32_e64 v157, -|v89|
	v_exp_f32_e64 v159, -|v73|
	v_cndmask_b32_e64 v207, 0, -v155, s[30:31]
	v_add_f32_e32 v157, 1.0, v157
	v_log_f32_e32 v157, v157
	v_add_f32_e32 v159, 1.0, v159
	v_log_f32_e32 v159, v159
	v_max_f32_e32 v155, 0, v89
	v_add_f32_e32 v155, v155, v157
	v_max_f32_e32 v157, 0, v73
	v_add_f32_e32 v157, v157, v159
	v_cndmask_b32_e64 v211, 0, -v157, s[42:43]
	v_exp_f32_e64 v157, -|v90|
	v_exp_f32_e64 v159, -|v74|
	v_cndmask_b32_e64 v210, 0, -v155, s[40:41]
	v_add_f32_e32 v157, 1.0, v157
	v_log_f32_e32 v157, v157
	v_add_f32_e32 v159, 1.0, v159
	v_log_f32_e32 v159, v159
	v_max_f32_e32 v155, 0, v90
	v_add_f32_e32 v155, v155, v157
	v_max_f32_e32 v157, 0, v74
	v_add_f32_e32 v157, v157, v159
	v_cndmask_b32_e64 v162, 0, -v157, s[38:39]
	v_exp_f32_e64 v157, -|v91|
	v_exp_f32_e64 v159, -|v75|
	v_cndmask_b32_e64 v209, 0, -v155, s[36:37]
	v_add_f32_e32 v157, 1.0, v157
	v_log_f32_e32 v157, v157
	v_add_f32_e32 v159, 1.0, v159
	v_log_f32_e32 v159, v159
	v_max_f32_e32 v155, 0, v91
	v_add_f32_e32 v155, v155, v157
	v_max_f32_e32 v157, 0, v75
	v_add_f32_e32 v157, v157, v159
	v_cndmask_b32_e64 v164, 0, -v157, s[46:47]
	v_exp_f32_e64 v157, -|v92|
	v_exp_f32_e64 v159, -|v76|
	v_cndmask_b32_e64 v212, 0, -v155, s[44:45]
	v_add_f32_e32 v157, 1.0, v157
	v_log_f32_e32 v157, v157
	v_add_f32_e32 v159, 1.0, v159
	v_log_f32_e32 v159, v159
	v_max_f32_e32 v155, 0, v92
	v_add_f32_e32 v155, v155, v157
	v_max_f32_e32 v157, 0, v76
	v_add_f32_e32 v157, v157, v159
	v_cndmask_b32_e64 v214, 0, -v157, s[50:51]
	v_exp_f32_e64 v157, -|v93|
	v_exp_f32_e64 v159, -|v77|
	v_cndmask_b32_e64 v213, 0, -v155, s[48:49]
	v_add_f32_e32 v157, 1.0, v157
	v_log_f32_e32 v157, v157
	v_add_f32_e32 v159, 1.0, v159
	v_log_f32_e32 v159, v159
	v_max_f32_e32 v155, 0, v93
	v_add_f32_e32 v155, v155, v157
	v_max_f32_e32 v157, 0, v77
	v_add_f32_e32 v157, v157, v159
	v_cndmask_b32_e64 v217, 0, -v157, s[58:59]
	v_exp_f32_e64 v157, -|v94|
	v_exp_f32_e64 v159, -|v78|
	v_cndmask_b32_e64 v216, 0, -v155, s[56:57]
	v_add_f32_e32 v157, 1.0, v157
	v_log_f32_e32 v157, v157
	v_add_f32_e32 v159, 1.0, v159
	v_log_f32_e32 v159, v159
	v_max_f32_e32 v155, 0, v94
	v_add_f32_e32 v155, v155, v157
	v_max_f32_e32 v157, 0, v78
	v_add_f32_e32 v157, v157, v159
	v_cndmask_b32_e64 v215, 0, -v157, s[54:55]
	v_exp_f32_e64 v157, -|v95|
	v_exp_f32_e64 v159, -|v79|
	v_cndmask_b32_e64 v168, 0, -v155, s[52:53]
	v_add_f32_e32 v157, 1.0, v157
	v_log_f32_e32 v157, v157
	v_add_f32_e32 v159, 1.0, v159
	v_log_f32_e32 v159, v159
	v_max_f32_e32 v155, 0, v95
	v_add_f32_e32 v155, v155, v157
	v_max_f32_e32 v157, 0, v79
	v_add_f32_e32 v157, v157, v159
	v_cndmask_b32_e64 v220, 0, -v157, s[62:63]
	v_exp_f32_e64 v157, -|v96|
	v_exp_f32_e64 v159, -|v80|
	v_cndmask_b32_e64 v170, 0, -v155, s[60:61]
	v_add_f32_e32 v157, 1.0, v157
	v_log_f32_e32 v157, v157
	v_add_f32_e32 v159, 1.0, v159
	v_log_f32_e32 v159, v159
	v_max_f32_e32 v155, 0, v96
	v_add_f32_e32 v155, v155, v157
	v_max_f32_e32 v157, 0, v80
	v_add_f32_e32 v157, v157, v159
	v_cndmask_b32_e64 v221, 0, -v157, s[66:67]
	v_exp_f32_e64 v157, -|v97|
	v_exp_f32_e64 v159, -|v81|
	v_cndmask_b32_e64 v172, 0, -v155, s[64:65]
	v_add_f32_e32 v157, 1.0, v157
	v_log_f32_e32 v157, v157
	v_add_f32_e32 v159, 1.0, v159
	v_log_f32_e32 v159, v159
	v_max_f32_e32 v155, 0, v97
	v_add_f32_e32 v155, v155, v157
	v_max_f32_e32 v157, 0, v81
	v_cndmask_b32_e64 v174, 0, -v155, s[68:69]
	v_add_f32_e32 v155, v201, v204
	v_add_f32_e32 v157, v157, v159
	v_add_f32_e32 v169, v0, v155
	v_add_f32_e32 v0, v202, v205
	v_add_f32_e32 v155, v207, v210
	v_cndmask_b32_e64 v222, 0, -v157, s[70:71]
	v_add_f32_e32 v155, v0, v155
	v_add_f32_e32 v0, v203, v206
	v_add_f32_e32 v157, v208, v211
	v_add_f32_e32 v159, v0, v157
	v_add_f32_e32 v0, v209, v212
	v_add_f32_e32 v157, v213, v216
	v_add_f32_e32 v223, v0, v157
	v_mov_b32_e32 v0, v155
	v_mov_b32_e32 v157, v155
	s_nop 1
	v_permlane32_swap_b32_e32 v0, v157
	v_cndmask_b32_e64 v157, v0, v157, s[4:5]
	v_mov_b32_e32 v0, v223
	v_mov_b32_e32 v161, v223
	s_nop 1
	v_permlane32_swap_b32_e32 v0, v161
	v_cndmask_b32_e64 v224, v0, v161, s[4:5]
	v_mov_b32_e32 v0, v169
	v_mov_b32_e32 v161, v169
	s_nop 1
	v_permlane32_swap_b32_e32 v0, v161
	v_add_f32_e32 v163, v215, v220
	v_add_f32_e32 v165, v221, v222
	v_cndmask_b32_e64 v171, v0, v161, s[4:5]
	v_mov_b32_e32 v0, v159
	v_mov_b32_e32 v161, v159
	s_nop 1
	v_permlane32_swap_b32_e32 v0, v161
	v_pk_add_f32 v[218:219], v[162:163], v[164:165]
	v_cndmask_b32_e64 v161, v0, v161, s[4:5]
	v_mov_b32_e32 v0, v219
	v_mov_b32_e32 v163, v219
	s_nop 1
	v_permlane32_swap_b32_e32 v0, v163
	v_add_f32_e32 v176, v214, v217
	v_cndmask_b32_e64 v177, v0, v163, s[4:5]
	v_pk_add_f32 v[218:219], v[218:219], v[176:177]
	v_add_f32_e32 v173, v159, v161
	v_mov_b32_e32 v0, v218
	v_mov_b32_e32 v163, v218
	s_nop 1
	v_permlane32_swap_b32_e32 v0, v163
	v_cndmask_b32_e64 v0, v0, v163, s[4:5]
	v_add_f32_e32 v163, 0, v177
	v_cndmask_b32_e64 v165, 0, v0, s[4:5]
	v_pk_add_f32 v[176:177], v[218:219], v[0:1]
	v_pk_add_f32 v[218:219], v[168:169], v[170:171]
	v_add_f32_e32 v0, v165, v177
	v_pk_add_f32 v[176:177], v[176:177], v[176:177] op_sel:[0,1] op_sel_hi:[1,0]
	v_cndmask_b32_e64 v165, 0, v161, s[4:5]
	v_mov_b32_e32 v175, v176
	v_add_f32_e32 v165, v165, v176
; #define SBAR() __builtin_amdgcn_sched_barrier(0)
; __device__ __forceinline__ void sb_block(const bf16* Qb, const bf16* Kh, const bf16* Vh, bf16* Ob, int q0, char* lds) {
;     ...
;             for (int k = 7; k >= 0; --k) { E[k] = acc + (hi == 0 ? ot[k] : 0.f); acc += gs[k] + ot[k]; }
; #pragma unroll
;             for (int k = 0; k < 4; ++k) {
;                 float s0 = E[k] + R, s1 = E[4 + k] + R;
; #pragma unroll
;                 for (int q = 3; q >= 0; --q) { const int r = 4 * k + q, c = (r & 3) + 8 * (r >> 2);
;                     s0 += l0[r]; s1 += l1[r];
;                     const float w0 = __builtin_amdgcn_exp2f(p0[r] + s0), w1 = __builtin_amdgcn_exp2f(p1[r] + s1);
;                     p0[r] = (c < dq) ? w0 : 0.f; p1[r] = (c + 32 < dq) ? w1 : 0.f; }
;             }
;             R += acc;
;             bf16x8 pa0, pa1, pa2, pa3;
;     ...
;             PK4(p0, 0, pa0); PK4(p0, 8, pa1); PK4(p1, 0, pa2); PK4(p1, 8, pa3);
;     ...
;             SBAR();
;             pv_tile<0, false>(o, vb0 + buf * SHM_V, pa0, pa1, pa2, pa3, true);
	v_pk_add_f32 v[176:177], v[172:173], v[174:175]
	v_cndmask_b32_e64 v159, 0, v171, s[4:5]
	v_pk_add_f32 v[218:219], v[218:219], v[176:177]
	v_cndmask_b32_e64 v175, 0, v157, s[4:5]
	v_mov_b32_e32 v161, v218
	v_mov_b32_e32 v169, v218
	s_nop 1
	v_permlane32_swap_b32_e32 v161, v169
	v_cndmask_b32_e64 v161, v161, v169, s[4:5]
	v_add_f32_e32 v169, v159, v177
	v_cndmask_b32_e64 v159, 0, v161, s[4:5]
	v_add_f32_e32 v171, v159, v219
	v_add_f32_e32 v159, v218, v161
	v_add_f32_e32 v161, v159, v219
	v_cndmask_b32_e64 v159, 0, v224, s[4:5]
	v_add_f32_e32 v173, v159, v161
	v_add_f32_e32 v159, v223, v224
	v_pk_add_f32 v[218:219], v[158:159], v[160:161]
	v_pk_add_f32 v[176:177], v[154:155], v[156:157]
	v_add_f32_e32 v161, v198, v169
	v_pk_add_f32 v[176:177], v[176:177], v[218:219]
	v_add_f32_e32 v0, v198, v0
	v_mov_b32_e32 v155, v176
	v_mov_b32_e32 v157, v176
	s_nop 1
	v_permlane32_swap_b32_e32 v155, v157
	v_cndmask_b32_e64 v155, v155, v157, s[4:5]
	v_cndmask_b32_e64 v159, 0, v155, s[4:5]
	v_add_f32_e32 v159, v159, v177
	v_add_f32_e32 v159, v198, v159
	v_add_f32_e32 v159, v160, v159
	v_add_f32_e32 v160, v204, v161
	v_add_f32_e32 v69, v69, v160
	v_exp_f32_e32 v69, v69
	v_add_f32_e32 v85, v85, v159
	v_add_f32_e32 v157, v175, v219
	v_add_f32_e32 v0, v217, v0
	v_cndmask_b32_e64 v161, 0, v69, s[24:25]
	v_add_f32_e32 v69, v158, v159
	v_add_f32_e32 v158, v201, v160
	v_add_f32_e32 v68, v68, v158
	v_exp_f32_e32 v68, v68
	v_add_f32_e32 v84, v84, v69
	v_cndmask_b32_e64 v163, 0, v163, s[4:5]
	v_exp_f32_e32 v85, v85
	v_cndmask_b32_e64 v159, 0, v68, s[16:17]
	v_add_f32_e32 v68, v156, v69
	v_add_f32_e32 v69, v200, v158
	v_add_f32_e32 v67, v67, v69
	v_exp_f32_e32 v67, v67
	v_add_f32_e32 v83, v83, v68
	v_exp_f32_e32 v84, v84
	v_exp_f32_e32 v83, v83
	v_cndmask_b32_e64 v156, 0, v67, s[12:13]
	v_add_f32_e32 v67, v154, v68
	v_add_f32_e32 v68, v199, v69
	v_add_f32_e32 v66, v66, v68
	v_exp_f32_e32 v66, v66
	v_add_f32_e32 v68, v198, v165
	v_add_f32_e32 v68, v211, v68
	v_add_f32_e32 v73, v73, v68
	v_add_f32_e32 v68, v208, v68
	v_exp_f32_e32 v73, v73
	v_add_f32_e32 v72, v72, v68
	v_add_f32_e32 v67, v82, v67
	v_cndmask_b32_e64 v82, 0, v66, s[8:9]
	v_add_f32_e32 v66, v198, v157
	v_exp_f32_e32 v72, v72
	v_add_f32_e32 v66, v210, v66
	v_add_f32_e32 v69, v89, v66
	v_add_f32_e32 v66, v207, v66
	v_cndmask_b32_e64 v89, 0, v73, s[42:43]
	v_add_f32_e32 v73, v88, v66
	v_add_f32_e32 v66, v205, v66
	v_cndmask_b32_e64 v88, 0, v72, s[34:35]
	v_add_f32_e32 v72, v87, v66
	v_add_f32_e32 v66, v202, v66
	v_add_f32_e32 v68, v206, v68
	v_add_f32_e32 v66, v86, v66
	v_add_f32_e32 v71, v71, v68
	v_add_f32_e32 v68, v203, v68
	v_exp_f32_e32 v66, v66
	v_add_f32_e32 v68, v70, v68
	v_exp_f32_e32 v68, v68
	v_exp_f32_e32 v71, v71
	v_cndmask_b32_e64 v70, 0, v66, s[18:19]
	v_add_f32_e32 v66, v198, v173
	v_add_f32_e32 v66, v216, v66
	v_cndmask_b32_e64 v86, 0, v68, s[20:21]
	v_add_f32_e32 v68, v93, v66
	v_exp_f32_e32 v68, v68
	v_cndmask_b32_e64 v87, 0, v71, s[28:29]
	v_add_f32_e32 v71, v77, v0
	v_add_f32_e32 v66, v213, v66
	v_exp_f32_e32 v71, v71
	v_cndmask_b32_e64 v77, 0, v68, s[56:57]
	v_add_f32_e32 v68, v92, v66
	v_exp_f32_e32 v68, v68
	v_add_f32_e32 v0, v214, v0
	v_cndmask_b32_e64 v93, 0, v71, s[58:59]
	v_add_f32_e32 v71, v76, v0
	v_add_f32_e32 v66, v212, v66
	v_exp_f32_e32 v71, v71
	v_cndmask_b32_e64 v76, 0, v68, s[48:49]
	v_add_f32_e32 v68, v91, v66
	v_exp_f32_e32 v68, v68
	v_add_f32_e32 v0, v164, v0
	v_add_f32_e32 v66, v209, v66
	v_cndmask_b32_e64 v92, 0, v71, s[50:51]
	v_add_f32_e32 v71, v75, v0
	v_add_f32_e32 v66, v90, v66
	v_exp_f32_e32 v71, v71
	v_cndmask_b32_e64 v75, 0, v68, s[44:45]
	v_exp_f32_e32 v66, v66
	v_add_f32_e32 v68, v198, v163
	v_add_f32_e32 v68, v222, v68
	v_add_f32_e32 v81, v81, v68
	v_add_f32_e32 v68, v221, v68
	v_add_f32_e32 v80, v80, v68
	v_cndmask_b32_e64 v91, 0, v71, s[46:47]
	v_cndmask_b32_e64 v71, 0, v66, s[36:37]
	v_add_f32_e32 v66, v198, v171
	v_exp_f32_e32 v80, v80
	v_add_f32_e32 v0, v162, v0
	v_add_f32_e32 v66, v174, v66
	v_add_f32_e32 v0, v74, v0
	v_add_f32_e32 v74, v97, v66
	v_add_f32_e32 v66, v172, v66
	v_add_f32_e32 v90, v96, v66
	v_add_f32_e32 v66, v170, v66
	v_add_f32_e32 v68, v220, v68
	v_cndmask_b32_e64 v96, 0, v80, s[66:67]
	v_add_f32_e32 v80, v95, v66
	v_add_f32_e32 v79, v79, v68
	v_add_f32_e32 v66, v168, v66
	v_add_f32_e32 v68, v215, v68
	v_add_f32_e32 v66, v94, v66
	v_add_f32_e32 v68, v78, v68
	v_exp_f32_e32 v67, v67
	v_exp_f32_e32 v69, v69
	v_exp_f32_e32 v73, v73
	v_exp_f32_e32 v72, v72
	v_exp_f32_e32 v0, v0
	v_exp_f32_e32 v74, v74
	v_exp_f32_e32 v81, v81
	v_exp_f32_e32 v90, v90
	v_exp_f32_e32 v80, v80
	v_exp_f32_e32 v79, v79
	v_exp_f32_e32 v66, v66
	v_exp_f32_e32 v68, v68
	v_add_f32_e32 v155, v176, v155
	v_cndmask_b32_e64 v85, 0, v85, s[22:23]
	v_cndmask_b32_e64 v84, 0, v84, s[14:15]
	v_cndmask_b32_e64 v83, 0, v83, s[10:11]
	v_cndmask_b32_e32 v67, 0, v67, vcc
	v_cndmask_b32_e64 v69, 0, v69, s[40:41]
	v_cndmask_b32_e64 v73, 0, v73, s[30:31]
	v_cndmask_b32_e64 v72, 0, v72, s[26:27]
	v_cndmask_b32_e64 v0, 0, v0, s[38:39]
	v_cndmask_b32_e64 v74, 0, v74, s[68:69]
	v_cndmask_b32_e64 v81, 0, v81, s[70:71]
	v_cndmask_b32_e64 v90, 0, v90, s[64:65]
	v_cndmask_b32_e64 v80, 0, v80, s[60:61]
	v_cndmask_b32_e64 v95, 0, v79, s[62:63]
	v_cndmask_b32_e64 v78, 0, v66, s[52:53]
	v_cndmask_b32_e64 v94, 0, v68, s[54:55]
	v_add_f32_e32 v66, v155, v177
	v_add_f32_e32 v198, v198, v66
	v_cvt_pk_bf16_f32 v66, v67, v83
	v_cvt_pk_bf16_f32 v67, v84, v85
	v_cvt_pk_bf16_f32 v68, v70, v72
	v_cvt_pk_bf16_f32 v69, v73, v69
	v_cvt_pk_bf16_f32 v70, v71, v75
	v_cvt_pk_bf16_f32 v71, v76, v77
	v_cvt_pk_bf16_f32 v72, v78, v80
	v_cvt_pk_bf16_f32 v73, v90, v74
	v_cvt_pk_bf16_f32 v74, v82, v156
	v_cvt_pk_bf16_f32 v75, v159, v161
	v_cvt_pk_bf16_f32 v76, v86, v87
	v_cvt_pk_bf16_f32 v77, v88, v89
	v_cvt_pk_bf16_f32 v78, v0, v91
	v_cvt_pk_bf16_f32 v79, v92, v93
	v_cvt_pk_bf16_f32 v80, v94, v95
	v_cvt_pk_bf16_f32 v81, v96, v81
	v_permlane32_swap_b32_e32 v66, v68
	v_permlane32_swap_b32_e32 v67, v69
	v_permlane32_swap_b32_e32 v70, v72
	v_permlane32_swap_b32_e32 v71, v73
	v_permlane32_swap_b32_e32 v74, v76
	v_permlane32_swap_b32_e32 v75, v77
	v_permlane32_swap_b32_e32 v78, v80
	v_permlane32_swap_b32_e32 v79, v81
	v_add_u32_e32 v0, s33, v197
	ds_read_b64_tr_b16 v[82:83], v0 offset:0
	ds_read_b64_tr_b16 v[84:85], v0 offset:0x800
	ds_read_b64_tr_b16 v[86:87], v0 offset:0x1000
	ds_read_b64_tr_b16 v[88:89], v0 offset:0x1800
	ds_read_b64_tr_b16 v[90:91], v0 offset:0x2000
	ds_read_b64_tr_b16 v[92:93], v0 offset:0x2800
	ds_read_b64_tr_b16 v[94:95], v0 offset:0x3000
	ds_read_b64_tr_b16 v[96:97], v0 offset:0x3800
	s_waitcnt lgkmcnt(0)
; template <int VB, bool SK>
; __device__ __forceinline__ void pv_tile(f32x16* o, int vb0, bf16x8 pa0, bf16x8 pa1, bf16x8 pa2, bf16x8 pa3, bool act) {
;     ...
;     PV_D0(0); PV_D0(1); PV_D0(2); PV_D0(3);
; __device__ __forceinline__ void sb_block(const bf16* Qb, const bf16* Kh, const bf16* Vh, bf16* Ob, int q0, char* lds) {
;     ...
;             wdone = __all(R < SB_STOP);
;         }
;         if (lane == 0) flags[(it & 1) * 8 + wid] = wdone ? 1 : 0;
	s_nop 0
	v_mfma_f32_32x32x16_bf16 v[2:17], v[66:69], v[82:85], v[2:17]
	ds_read_b64_tr_b16 v[82:83], v0 offset:0x200
	ds_read_b64_tr_b16 v[84:85], v0 offset:0xa00
	v_mfma_f32_32x32x16_bf16 v[2:17], v[70:73], v[86:89], v[2:17]
	ds_read_b64_tr_b16 v[86:87], v0 offset:0x1200
	ds_read_b64_tr_b16 v[88:89], v0 offset:0x1a00
	v_mfma_f32_32x32x16_bf16 v[2:17], v[74:77], v[90:93], v[2:17]
	ds_read_b64_tr_b16 v[90:91], v0 offset:0x2200
	ds_read_b64_tr_b16 v[92:93], v0 offset:0x2a00
	ds_read_b64_tr_b16 v[154:155], v0 offset:0x3200
	ds_read_b64_tr_b16 v[156:157], v0 offset:0x3a00
	s_waitcnt lgkmcnt(0)
	v_mfma_f32_32x32x16_bf16 v[2:17], v[78:81], v[94:97], v[2:17]
	v_mfma_f32_32x32x16_bf16 v[18:33], v[66:69], v[82:85], v[18:33]
	ds_read_b64_tr_b16 v[82:83], v0 offset:0x400
	ds_read_b64_tr_b16 v[84:85], v0 offset:0xc00
	v_mfma_f32_32x32x16_bf16 v[18:33], v[70:73], v[86:89], v[18:33]
	ds_read_b64_tr_b16 v[86:87], v0 offset:0x1400
	ds_read_b64_tr_b16 v[88:89], v0 offset:0x1c00
	v_mfma_f32_32x32x16_bf16 v[18:33], v[74:77], v[90:93], v[18:33]
	ds_read_b64_tr_b16 v[90:91], v0 offset:0x2400
	ds_read_b64_tr_b16 v[92:93], v0 offset:0x2c00
	ds_read_b64_tr_b16 v[94:95], v0 offset:0x3400
	ds_read_b64_tr_b16 v[96:97], v0 offset:0x3c00
	s_waitcnt lgkmcnt(0)
	v_mfma_f32_32x32x16_bf16 v[18:33], v[78:81], v[154:157], v[18:33]
	v_mfma_f32_32x32x16_bf16 v[34:49], v[66:69], v[82:85], v[34:49]
	ds_read_b64_tr_b16 v[82:83], v0 offset:0x600
	ds_read_b64_tr_b16 v[84:85], v0 offset:0xe00
	v_mfma_f32_32x32x16_bf16 v[34:49], v[70:73], v[86:89], v[34:49]
	ds_read_b64_tr_b16 v[86:87], v0 offset:0x1600
	ds_read_b64_tr_b16 v[88:89], v0 offset:0x1e00
	v_mfma_f32_32x32x16_bf16 v[34:49], v[74:77], v[90:93], v[34:49]
	ds_read_b64_tr_b16 v[90:91], v0 offset:0x2600
	ds_read_b64_tr_b16 v[92:93], v0 offset:0x2e00
	ds_read_b64_tr_b16 v[154:155], v0 offset:0x3600
	ds_read_b64_tr_b16 v[156:157], v0 offset:0x3e00
	s_waitcnt lgkmcnt(0)
	v_mfma_f32_32x32x16_bf16 v[34:49], v[78:81], v[94:97], v[34:49]
	v_mfma_f32_32x32x16_bf16 v[50:65], v[66:69], v[82:85], v[50:65]
	v_cmp_gt_f32_e32 vcc, s79, v198
	s_cmp_eq_u64 vcc, exec
	s_cselect_b64 s[8:9], -1, 0
	v_mfma_f32_32x32x16_bf16 v[50:65], v[70:73], v[86:89], v[50:65]
	v_mfma_f32_32x32x16_bf16 v[50:65], v[74:77], v[90:93], v[50:65]
	v_mfma_f32_32x32x16_bf16 v[50:65], v[78:81], v[154:157], v[50:65]
	s_and_saveexec_b64 s[10:11], s[6:7]
	s_cbranch_execz .LBB0_698

; __device__ __forceinline__ unsigned pk2(float lo, float hi) { return pg8::cvt_pk_bf16(lo, hi); }
;     __device__ __forceinline__ void operator()(const pg8::f32x4 (&acc)[2][2][4][2], const pg8::Unit& u, int wr, int wc, int fr, int fq) const {
;     ...
;         for (int ai = 0; ai < 2; ++ai)
; #pragma unroll
;             for (int m = 0; m < 4; ++m) {
;                 const int row = u.pm * 256 + ai * 128 + wr * 64 + m * 16 + fr;
;                 const int bb = row >> 13, ss = row & 8191;
;                 float ssq = 0.f;
;                 float rs = 1.f;
;                 if constexpr (KIND == EK_Q || KIND == EK_KV) rs = __builtin_amdgcn_rsqf(a.ssq0[row] * (1.f / 512.f) + EPS);
;                 if constexpr (KIND == EK_FIN) rs = __builtin_amdgcn_rsqf(a.ssq0[row] * (1.f / 2048.f) + EPS);
; #pragma unroll
;                 for (int bj = 0; bj < 2; ++bj) {
;                     const int cl = bj * 128 + wc * 32 + fq * 8;
;                     float v[8];
; #pragma unroll
;                     for (int j = 0; j < 4; ++j) { v[j] = acc[ai][bj][m][0][j]; v[4 + j] = acc[ai][bj][m][1][j]; }
;     ...
;                     } else if constexpr (KIND == EK_UP) {
; #pragma unroll
;                         for (int j = 0; j < 8; ++j) { const float r = fmaxf(v[j], 0.f); v[j] = r * r; }
;                         { u32x4 w; w.x = pk2(v[0], v[1]); w.y = pk2(v[2], v[3]); w.z = pk2(v[4], v[5]); w.w = pk2(v[6], v[7]); __builtin_nontemporal_store(w, (u32x4*)(a.o0 + (size_t)row * FF + pn * 256 + cl)); }
.LBB0_1297:
	v_lshl_add_u32 v146, s26, 8, v148
	v_max_f32_e32 v120, 0, v120
	v_max_f32_e32 v121, 0, v121
	s_lshl_b32 s26, s27, 8
	v_ashrrev_i32_e32 v147, 31, v146
	v_max_f32_e32 v124, 0, v124
	v_max_f32_e32 v125, 0, v125
	v_pk_mul_f32 v[156:157], v[120:121], v[120:121]
	s_ashr_i32 s27, s26, 31
	v_lshlrev_b64 v[154:155], 14, v[146:147]
	v_pk_mul_f32 v[124:125], v[124:125], v[124:125]
	v_max_f32_e32 v120, 0, v122
	v_max_f32_e32 v121, 0, v123
	v_max_f32_e32 v126, 0, v126
	v_max_f32_e32 v127, 0, v127
	v_pk_mul_f32 v[158:159], v[120:121], v[120:121]
	v_cvt_pk_bf16_f32 v120, v124, v125
	v_lshl_add_u64 v[124:125], s[12:13], 0, v[154:155]
	s_lshl_b64 s[26:27], s[26:27], 1
	v_pk_mul_f32 v[126:127], v[126:127], v[126:127]
	v_lshl_add_u64 v[124:125], v[124:125], 0, s[26:27]
	v_cvt_pk_bf16_f32 v121, v126, v127
	v_cvt_pk_bf16_f32 v122, v156, v157
	v_cvt_pk_bf16_f32 v123, v158, v159
	v_lshl_add_u64 v[124:125], v[124:125], 0, v[136:137]
	v_max_f32_e32 v108, 0, v108
	v_max_f32_e32 v109, 0, v109
	global_store_dwordx4 v[124:125], v[120:123], off nt
	s_nop 1
	v_pk_mul_f32 v[120:121], v[108:109], v[108:109]
	v_max_f32_e32 v116, 0, v116
	v_max_f32_e32 v117, 0, v117
	v_max_f32_e32 v118, 0, v118
	v_max_f32_e32 v119, 0, v119
	v_max_f32_e32 v108, 0, v110
	v_max_f32_e32 v109, 0, v111
	v_pk_mul_f32 v[116:117], v[116:117], v[116:117]
	v_pk_mul_f32 v[118:119], v[118:119], v[118:119]
	v_pk_mul_f32 v[122:123], v[108:109], v[108:109]
	v_cvt_pk_bf16_f32 v108, v116, v117
	v_cvt_pk_bf16_f32 v109, v118, v119
	v_cvt_pk_bf16_f32 v110, v120, v121
	v_cvt_pk_bf16_f32 v111, v122, v123
	global_store_dwordx4 v[124:125], v[108:111], off offset:256 nt
	s_nop 1
	v_or_b32_e32 v108, 16, v146
	v_ashrrev_i32_e32 v109, 31, v108
	v_max_f32_e32 v104, 0, v104
	v_max_f32_e32 v105, 0, v105
	v_lshlrev_b64 v[108:109], 14, v[108:109]
	v_max_f32_e32 v110, v112, v112
	v_max_f32_e32 v111, v113, v113
	v_max_f32_e32 v112, v114, v114
	v_max_f32_e32 v113, v115, v115
	v_pk_mul_f32 v[114:115], v[104:105], v[104:105]
	v_max_f32_e32 v110, 0, v110
	v_max_f32_e32 v111, 0, v111
	v_max_f32_e32 v112, 0, v112
	v_max_f32_e32 v113, 0, v113
	v_max_f32_e32 v104, 0, v106
	v_max_f32_e32 v105, 0, v107
	v_lshl_add_u64 v[108:109], s[12:13], 0, v[108:109]
	v_pk_mul_f32 v[110:111], v[110:111], v[110:111]
	v_pk_mul_f32 v[112:113], v[112:113], v[112:113]
	v_pk_mul_f32 v[116:117], v[104:105], v[104:105]
	v_lshl_add_u64 v[108:109], v[108:109], 0, s[26:27]
	v_cvt_pk_bf16_f32 v104, v110, v111
	v_cvt_pk_bf16_f32 v105, v112, v113
	v_cvt_pk_bf16_f32 v106, v114, v115
	v_cvt_pk_bf16_f32 v107, v116, v117
	v_lshl_add_u64 v[108:109], v[108:109], 0, v[136:137]
	v_max_f32_e32 v92, 0, v92
	v_max_f32_e32 v93, 0, v93
	global_store_dwordx4 v[108:109], v[104:107], off nt
	s_nop 1
	v_pk_mul_f32 v[104:105], v[92:93], v[92:93]
	v_max_f32_e32 v100, 0, v100
	v_max_f32_e32 v101, 0, v101
	v_max_f32_e32 v102, 0, v102
	v_max_f32_e32 v103, 0, v103
	v_max_f32_e32 v92, 0, v94
	v_max_f32_e32 v93, 0, v95
	v_pk_mul_f32 v[100:101], v[100:101], v[100:101]
	v_pk_mul_f32 v[102:103], v[102:103], v[102:103]
	v_pk_mul_f32 v[106:107], v[92:93], v[92:93]
	v_cvt_pk_bf16_f32 v92, v100, v101
	v_cvt_pk_bf16_f32 v93, v102, v103
	v_cvt_pk_bf16_f32 v94, v104, v105
	v_cvt_pk_bf16_f32 v95, v106, v107
	global_store_dwordx4 v[108:109], v[92:95], off offset:256 nt
	s_nop 1
	v_or_b32_e32 v92, 32, v146
	v_ashrrev_i32_e32 v93, 31, v92
	v_max_f32_e32 v88, 0, v88
	v_max_f32_e32 v89, 0, v89
	v_lshlrev_b64 v[92:93], 14, v[92:93]
	v_max_f32_e32 v94, v96, v96
	v_max_f32_e32 v95, v97, v97
	v_max_f32_e32 v96, v98, v98
	v_max_f32_e32 v97, v99, v99
	v_pk_mul_f32 v[98:99], v[88:89], v[88:89]
	v_max_f32_e32 v94, 0, v94
	v_max_f32_e32 v95, 0, v95
	v_max_f32_e32 v96, 0, v96
	v_max_f32_e32 v97, 0, v97
	v_max_f32_e32 v88, 0, v90
	v_max_f32_e32 v89, 0, v91
	v_lshl_add_u64 v[92:93], s[12:13], 0, v[92:93]
	v_pk_mul_f32 v[94:95], v[94:95], v[94:95]
	v_pk_mul_f32 v[96:97], v[96:97], v[96:97]
	v_pk_mul_f32 v[100:101], v[88:89], v[88:89]
	v_lshl_add_u64 v[92:93], v[92:93], 0, s[26:27]
	v_cvt_pk_bf16_f32 v88, v94, v95
	v_cvt_pk_bf16_f32 v89, v96, v97
	v_cvt_pk_bf16_f32 v90, v98, v99
	v_cvt_pk_bf16_f32 v91, v100, v101
	v_lshl_add_u64 v[92:93], v[92:93], 0, v[136:137]
	v_max_f32_e32 v76, 0, v76
	v_max_f32_e32 v77, 0, v77
	global_store_dwordx4 v[92:93], v[88:91], off nt
	s_nop 1
	v_pk_mul_f32 v[88:89], v[76:77], v[76:77]
	v_max_f32_e32 v84, 0, v84
	v_max_f32_e32 v85, 0, v85
	v_max_f32_e32 v86, 0, v86
	v_max_f32_e32 v87, 0, v87
	v_max_f32_e32 v76, 0, v78
	v_max_f32_e32 v77, 0, v79
	v_pk_mul_f32 v[84:85], v[84:85], v[84:85]
	v_pk_mul_f32 v[86:87], v[86:87], v[86:87]
	v_pk_mul_f32 v[90:91], v[76:77], v[76:77]
	v_cvt_pk_bf16_f32 v76, v84, v85
	v_cvt_pk_bf16_f32 v77, v86, v87
	v_cvt_pk_bf16_f32 v78, v88, v89
	v_cvt_pk_bf16_f32 v79, v90, v91
	global_store_dwordx4 v[92:93], v[76:79], off offset:256 nt
	s_nop 1
	v_or_b32_e32 v76, 48, v146
	v_ashrrev_i32_e32 v77, 31, v76
	v_max_f32_e32 v72, 0, v72
	v_max_f32_e32 v73, 0, v73
	v_lshlrev_b64 v[76:77], 14, v[76:77]
	v_max_f32_e32 v78, v80, v80
	v_max_f32_e32 v79, v81, v81
	v_max_f32_e32 v80, v82, v82
	v_max_f32_e32 v81, v83, v83
	v_pk_mul_f32 v[82:83], v[72:73], v[72:73]
	v_max_f32_e32 v78, 0, v78
	v_max_f32_e32 v79, 0, v79
	v_max_f32_e32 v80, 0, v80
	v_max_f32_e32 v81, 0, v81
	v_max_f32_e32 v72, 0, v74
	v_max_f32_e32 v73, 0, v75
	v_lshl_add_u64 v[76:77], s[12:13], 0, v[76:77]
	v_pk_mul_f32 v[78:79], v[78:79], v[78:79]
	v_pk_mul_f32 v[80:81], v[80:81], v[80:81]
	v_pk_mul_f32 v[84:85], v[72:73], v[72:73]
	v_lshl_add_u64 v[76:77], v[76:77], 0, s[26:27]
	v_cvt_pk_bf16_f32 v72, v78, v79
	v_cvt_pk_bf16_f32 v73, v80, v81
	v_cvt_pk_bf16_f32 v74, v82, v83
	v_cvt_pk_bf16_f32 v75, v84, v85
; __device__ __forceinline__ unsigned pk2(float lo, float hi) { return pg8::cvt_pk_bf16(lo, hi); }
;     __device__ __forceinline__ void operator()(const pg8::f32x4 (&acc)[2][2][4][2], const pg8::Unit& u, int wr, int wc, int fr, int fq) const {
;     ...
;         for (int ai = 0; ai < 2; ++ai)
; #pragma unroll
;             for (int m = 0; m < 4; ++m) {
;                 const int row = u.pm * 256 + ai * 128 + wr * 64 + m * 16 + fr;
;                 const int bb = row >> 13, ss = row & 8191;
;                 float ssq = 0.f;
;                 float rs = 1.f;
;                 if constexpr (KIND == EK_Q || KIND == EK_KV) rs = __builtin_amdgcn_rsqf(a.ssq0[row] * (1.f / 512.f) + EPS);
;                 if constexpr (KIND == EK_FIN) rs = __builtin_amdgcn_rsqf(a.ssq0[row] * (1.f / 2048.f) + EPS);
; #pragma unroll
;                 for (int bj = 0; bj < 2; ++bj) {
;                     const int cl = bj * 128 + wc * 32 + fq * 8;
;                     float v[8];
; #pragma unroll
;                     for (int j = 0; j < 4; ++j) { v[j] = acc[ai][bj][m][0][j]; v[4 + j] = acc[ai][bj][m][1][j]; }
;     ...
;                     } else if constexpr (KIND == EK_UP) {
; #pragma unroll
;                         for (int j = 0; j < 8; ++j) { const float r = fmaxf(v[j], 0.f); v[j] = r * r; }
;                         { u32x4 w; w.x = pk2(v[0], v[1]); w.y = pk2(v[2], v[3]); w.z = pk2(v[4], v[5]); w.w = pk2(v[6], v[7]); __builtin_nontemporal_store(w, (u32x4*)(a.o0 + (size_t)row * FF + pn * 256 + cl)); }
	v_lshl_add_u64 v[76:77], v[76:77], 0, v[136:137]
	v_max_f32_e32 v64, 0, v64
	v_max_f32_e32 v65, 0, v65
	global_store_dwordx4 v[76:77], v[72:75], off nt
	s_nop 1
	v_pk_mul_f32 v[72:73], v[64:65], v[64:65]
	v_max_f32_e32 v68, 0, v68
	v_max_f32_e32 v69, 0, v69
	v_max_f32_e32 v70, 0, v70
	v_max_f32_e32 v71, 0, v71
	v_max_f32_e32 v64, 0, v66
	v_max_f32_e32 v65, 0, v67
	v_pk_mul_f32 v[68:69], v[68:69], v[68:69]
	v_pk_mul_f32 v[70:71], v[70:71], v[70:71]
	v_pk_mul_f32 v[74:75], v[64:65], v[64:65]
	v_cvt_pk_bf16_f32 v64, v68, v69
	v_cvt_pk_bf16_f32 v65, v70, v71
	v_cvt_pk_bf16_f32 v66, v72, v73
	v_cvt_pk_bf16_f32 v67, v74, v75
	global_store_dwordx4 v[76:77], v[64:67], off offset:256 nt
	s_nop 1
	v_add_u32_e32 v64, 0x80, v146
	v_max_f32_e32 v56, 0, v56
	v_max_f32_e32 v57, 0, v57
	v_ashrrev_i32_e32 v65, 31, v64
	v_max_f32_e32 v60, 0, v60
	v_max_f32_e32 v61, 0, v61
	v_pk_mul_f32 v[66:67], v[56:57], v[56:57]
	v_lshlrev_b64 v[64:65], 14, v[64:65]
	v_pk_mul_f32 v[60:61], v[60:61], v[60:61]
	v_max_f32_e32 v56, 0, v58
	v_max_f32_e32 v57, 0, v59
	v_max_f32_e32 v62, 0, v62
	v_max_f32_e32 v63, 0, v63
	v_pk_mul_f32 v[68:69], v[56:57], v[56:57]
	v_cvt_pk_bf16_f32 v56, v60, v61
	v_lshl_add_u64 v[60:61], s[12:13], 0, v[64:65]
	v_pk_mul_f32 v[62:63], v[62:63], v[62:63]
	v_lshl_add_u64 v[60:61], v[60:61], 0, s[26:27]
	v_cvt_pk_bf16_f32 v57, v62, v63
	v_cvt_pk_bf16_f32 v58, v66, v67
	v_cvt_pk_bf16_f32 v59, v68, v69
	v_lshl_add_u64 v[60:61], v[60:61], 0, v[136:137]
	v_max_f32_e32 v44, 0, v44
	v_max_f32_e32 v45, 0, v45
	global_store_dwordx4 v[60:61], v[56:59], off nt
	s_nop 1
	v_pk_mul_f32 v[56:57], v[44:45], v[44:45]
	v_max_f32_e32 v52, 0, v52
	v_max_f32_e32 v53, 0, v53
	v_max_f32_e32 v54, 0, v54
	v_max_f32_e32 v55, 0, v55
	v_max_f32_e32 v44, 0, v46
	v_max_f32_e32 v45, 0, v47
	v_pk_mul_f32 v[52:53], v[52:53], v[52:53]
	v_pk_mul_f32 v[54:55], v[54:55], v[54:55]
	v_pk_mul_f32 v[58:59], v[44:45], v[44:45]
	v_cvt_pk_bf16_f32 v44, v52, v53
	v_cvt_pk_bf16_f32 v45, v54, v55
	v_cvt_pk_bf16_f32 v46, v56, v57
	v_cvt_pk_bf16_f32 v47, v58, v59
	global_store_dwordx4 v[60:61], v[44:47], off offset:256 nt
	s_nop 1
	v_add_u32_e32 v44, 0x90, v146
	v_ashrrev_i32_e32 v45, 31, v44
	v_max_f32_e32 v40, 0, v40
	v_max_f32_e32 v41, 0, v41
	v_lshlrev_b64 v[44:45], 14, v[44:45]
	v_max_f32_e32 v46, v48, v48
	v_max_f32_e32 v47, v49, v49
	v_max_f32_e32 v48, v50, v50
	v_max_f32_e32 v49, v51, v51
	v_pk_mul_f32 v[50:51], v[40:41], v[40:41]
	v_max_f32_e32 v46, 0, v46
	v_max_f32_e32 v47, 0, v47
	v_max_f32_e32 v48, 0, v48
	v_max_f32_e32 v49, 0, v49
	v_max_f32_e32 v40, 0, v42
	v_max_f32_e32 v41, 0, v43
	v_lshl_add_u64 v[44:45], s[12:13], 0, v[44:45]
	v_pk_mul_f32 v[46:47], v[46:47], v[46:47]
	v_pk_mul_f32 v[48:49], v[48:49], v[48:49]
	v_pk_mul_f32 v[52:53], v[40:41], v[40:41]
	v_lshl_add_u64 v[44:45], v[44:45], 0, s[26:27]
	v_cvt_pk_bf16_f32 v40, v46, v47
	v_cvt_pk_bf16_f32 v41, v48, v49
	v_cvt_pk_bf16_f32 v42, v50, v51
	v_cvt_pk_bf16_f32 v43, v52, v53
	v_lshl_add_u64 v[44:45], v[44:45], 0, v[136:137]
	v_max_f32_e32 v28, 0, v28
	v_max_f32_e32 v29, 0, v29
	global_store_dwordx4 v[44:45], v[40:43], off nt
	s_nop 1
	v_pk_mul_f32 v[40:41], v[28:29], v[28:29]
	v_max_f32_e32 v36, 0, v36
	v_max_f32_e32 v37, 0, v37
	v_max_f32_e32 v38, 0, v38
	v_max_f32_e32 v39, 0, v39
	v_max_f32_e32 v28, 0, v30
	v_max_f32_e32 v29, 0, v31
	v_pk_mul_f32 v[36:37], v[36:37], v[36:37]
	v_pk_mul_f32 v[38:39], v[38:39], v[38:39]
	v_pk_mul_f32 v[42:43], v[28:29], v[28:29]
	v_cvt_pk_bf16_f32 v28, v36, v37
	v_cvt_pk_bf16_f32 v29, v38, v39
	v_cvt_pk_bf16_f32 v30, v40, v41
	v_cvt_pk_bf16_f32 v31, v42, v43
	global_store_dwordx4 v[44:45], v[28:31], off offset:256 nt
	s_nop 1
	v_add_u32_e32 v28, 0xa0, v146
	v_ashrrev_i32_e32 v29, 31, v28
	v_max_f32_e32 v24, 0, v24
	v_max_f32_e32 v25, 0, v25
	v_lshlrev_b64 v[28:29], 14, v[28:29]
	v_max_f32_e32 v30, v32, v32
	v_max_f32_e32 v31, v33, v33
	v_max_f32_e32 v32, v34, v34
	v_max_f32_e32 v33, v35, v35
	v_pk_mul_f32 v[34:35], v[24:25], v[24:25]
	v_max_f32_e32 v30, 0, v30
	v_max_f32_e32 v31, 0, v31
	v_max_f32_e32 v32, 0, v32
	v_max_f32_e32 v33, 0, v33
	v_max_f32_e32 v24, 0, v26
	v_max_f32_e32 v25, 0, v27
	v_lshl_add_u64 v[28:29], s[12:13], 0, v[28:29]
	v_pk_mul_f32 v[30:31], v[30:31], v[30:31]
	v_pk_mul_f32 v[32:33], v[32:33], v[32:33]
	v_pk_mul_f32 v[36:37], v[24:25], v[24:25]
	v_lshl_add_u64 v[28:29], v[28:29], 0, s[26:27]
	v_cvt_pk_bf16_f32 v24, v30, v31
	v_cvt_pk_bf16_f32 v25, v32, v33
	v_cvt_pk_bf16_f32 v26, v34, v35
	v_cvt_pk_bf16_f32 v27, v36, v37
	v_lshl_add_u64 v[28:29], v[28:29], 0, v[136:137]
	v_max_f32_e32 v12, 0, v12
	v_max_f32_e32 v13, 0, v13
	global_store_dwordx4 v[28:29], v[24:27], off nt
	s_nop 1
	v_pk_mul_f32 v[24:25], v[12:13], v[12:13]
	v_max_f32_e32 v20, 0, v20
	v_max_f32_e32 v21, 0, v21
	v_max_f32_e32 v22, 0, v22
	v_max_f32_e32 v23, 0, v23
	v_max_f32_e32 v12, 0, v14
	v_max_f32_e32 v13, 0, v15
	v_pk_mul_f32 v[20:21], v[20:21], v[20:21]
	v_pk_mul_f32 v[22:23], v[22:23], v[22:23]
	v_pk_mul_f32 v[26:27], v[12:13], v[12:13]
	v_cvt_pk_bf16_f32 v12, v20, v21
	v_cvt_pk_bf16_f32 v13, v22, v23
	v_cvt_pk_bf16_f32 v14, v24, v25
	v_cvt_pk_bf16_f32 v15, v26, v27
	global_store_dwordx4 v[28:29], v[12:15], off offset:256 nt
	s_nop 1
	v_add_u32_e32 v12, 0xb0, v146
	v_ashrrev_i32_e32 v13, 31, v12
	v_max_f32_e32 v8, 0, v8
	v_max_f32_e32 v9, 0, v9
	v_lshlrev_b64 v[12:13], 14, v[12:13]
	v_max_f32_e32 v14, v16, v16
	v_max_f32_e32 v15, v17, v17
	v_max_f32_e32 v16, v18, v18
	v_max_f32_e32 v17, v19, v19
	v_pk_mul_f32 v[18:19], v[8:9], v[8:9]
	v_max_f32_e32 v14, 0, v14
	v_max_f32_e32 v15, 0, v15
	v_max_f32_e32 v16, 0, v16
	v_max_f32_e32 v17, 0, v17
	v_max_f32_e32 v8, 0, v10
	v_max_f32_e32 v9, 0, v11
	v_lshl_add_u64 v[12:13], s[12:13], 0, v[12:13]
	v_pk_mul_f32 v[14:15], v[14:15], v[14:15]
	v_pk_mul_f32 v[16:17], v[16:17], v[16:17]
	v_pk_mul_f32 v[20:21], v[8:9], v[8:9]
	v_lshl_add_u64 v[12:13], v[12:13], 0, s[26:27]
	v_cvt_pk_bf16_f32 v8, v14, v15
	v_cvt_pk_bf16_f32 v9, v16, v17
	v_cvt_pk_bf16_f32 v10, v18, v19
	v_cvt_pk_bf16_f32 v11, v20, v21
	v_lshl_add_u64 v[12:13], v[12:13], 0, v[136:137]
	v_max_f32_e32 v0, 0, v0
	v_max_f32_e32 v1, 0, v1
	global_store_dwordx4 v[12:13], v[8:11], off nt
	s_nop 1
	v_pk_mul_f32 v[8:9], v[0:1], v[0:1]
	v_max_f32_e32 v4, 0, v4
	v_max_f32_e32 v5, 0, v5
	v_max_f32_e32 v6, 0, v6
	v_max_f32_e32 v7, 0, v7
	v_max_f32_e32 v0, 0, v2
	v_max_f32_e32 v1, 0, v3
	v_pk_mul_f32 v[4:5], v[4:5], v[4:5]
	v_pk_mul_f32 v[6:7], v[6:7], v[6:7]
	v_pk_mul_f32 v[10:11], v[0:1], v[0:1]
	v_cvt_pk_bf16_f32 v0, v4, v5
	v_cvt_pk_bf16_f32 v1, v6, v7
	v_cvt_pk_bf16_f32 v2, v8, v9
	v_cvt_pk_bf16_f32 v3, v10, v11
	s_andn2_b64 vcc, exec, s[8:9]
	s_mov_b64 s[8:9], -1
	global_store_dwordx4 v[12:13], v[0:3], off offset:256 nt
	s_cbranch_vccnz .LBB0_1286
	s_andn2_b64 vcc, exec, s[10:11]
	s_cbranch_vccnz .LBB0_1285
	s_barrier
	s_branch .LBB0_1285
